# v21 + the leading wave half runs each GEMM epilogue at s_setprio 1 (it still has the next tile's first load phase to do before the hand-off barrier); priority reset to 0 at the epilogue end
# speedup vs baseline: 1.0028x; 1.0028x over previous
; __device__ __forceinline__ u32x4 pack8(f32x4 a, f32x4 b) { u32x4 w; w.x = cvt_pk_bf16(a[0], a[1]); w.y = cvt_pk_bf16(a[2], a[3]); w.z = cvt_pk_bf16(b[0], b[1]); w.w = cvt_pk_bf16(b[2], b[3]); return w; }
; #define PG8_BAR __builtin_amdgcn_s_barrier()
; template <class Epi>
; __device__ __forceinline__ void gemm_phase(LAS unsigned char* lds, const Gemm g, const StaticOrder& S, const Epi& E, int wave_) {
;     ...
;         if (wr == 0) PG8_BAR;
;         E(acc, cur, wr, wc, fr, fq);
;         if (!has_next) break;
;     __device__ __forceinline__ void operator()(EP_ARGS) const {
;         const int t = u.pn >> 3; bf16_t* base = Q + (size_t)t * tstride; const float sc = t == 0 ? qscale : 1.0f; const int colt = (u.pn & 7) * 256 + wc * 32 + 8 * fq;
; #pragma unroll
;         for (int ai = 0; ai < 2; ++ai)
; #pragma unroll
;             for (int m = 0; m < 4; ++m) { const int row = EP_ROW(ai, m);
; #pragma unroll
;                 for (int bj = 0; bj < 2; ++bj) *(u32x4*)(base + (size_t)row * 2048 + colt + bj * HALF) = pack8(acc[ai][bj][m][0] * sc, acc[ai][bj][m][1] * sc); }
;     }
.Lpeel_exit_8:
	v_readlane_b32 s12, v253, 13
	v_readlane_b32 s13, v253, 14
	s_and_b64 vcc, exec, s[12:13]
	s_cbranch_vccz .LBB0_194
	s_barrier
	s_setprio 1
.LBB0_194:
	s_ashr_i32 s12, s44, 3
	s_ashr_i32 s13, s12, 31
	s_lshl_b64 s[12:13], s[12:13], 27
	s_add_u32 s12, s31, s12
	s_addc_u32 s13, s36, s13
	s_cmp_lt_u32 s44, 8
	s_cselect_b64 vcc, -1, 0
	s_lshl_b32 s5, s44, 8
	s_and_b32 s5, s5, 0x700
	v_or_b32_e32 v130, s5, v140
	v_lshl_add_u32 v132, s43, 8, v137
	v_mov_b32_e32 v128, 0x3e0293ee
	v_lshlrev_b32_e32 v184, 1, v130
	v_ashrrev_i32_e32 v133, 31, v132
	v_cndmask_b32_e32 v128, 1.0, v128, vcc
	v_lshl_add_u64 v[130:131], s[12:13], 0, v[184:185]
	v_lshlrev_b64 v[142:143], 12, v[132:133]
	v_lshl_add_u64 v[142:143], v[130:131], 0, v[142:143]
	v_pk_mul_f32 v[126:127], v[128:129], v[126:127] op_sel_hi:[0,1]
	v_pk_mul_f32 v[124:125], v[128:129], v[124:125] op_sel_hi:[0,1]
	v_pk_mul_f32 v[144:145], v[128:129], v[122:123] op_sel_hi:[0,1]
	v_pk_mul_f32 v[122:123], v[128:129], v[120:121] op_sel_hi:[0,1]
	v_cvt_pk_bf16_f32 v120, v124, v125
	v_cvt_pk_bf16_f32 v121, v126, v127
	v_cvt_pk_bf16_f32 v122, v122, v123
	v_cvt_pk_bf16_f32 v123, v144, v145
	flat_store_dwordx4 v[142:143], v[120:123]
	v_pk_mul_f32 v[116:117], v[128:129], v[116:117] op_sel_hi:[0,1]
	v_pk_mul_f32 v[118:119], v[128:129], v[118:119] op_sel_hi:[0,1]
	v_pk_mul_f32 v[120:121], v[128:129], v[110:111] op_sel_hi:[0,1]
	v_pk_mul_f32 v[110:111], v[128:129], v[108:109] op_sel_hi:[0,1]
	v_cvt_pk_bf16_f32 v108, v116, v117
	v_cvt_pk_bf16_f32 v109, v118, v119
	v_cvt_pk_bf16_f32 v110, v110, v111
	v_cvt_pk_bf16_f32 v111, v120, v121
	flat_store_dwordx4 v[142:143], v[108:111] offset:256
	v_pk_mul_f32 v[112:113], v[128:129], v[112:113] op_sel_hi:[0,1]
	v_pk_mul_f32 v[100:101], v[128:129], v[100:101] op_sel_hi:[0,1]
	v_or_b32_e32 v108, 16, v132
	v_ashrrev_i32_e32 v109, 31, v108
	v_lshlrev_b64 v[108:109], 12, v[108:109]
	v_lshl_add_u64 v[108:109], v[130:131], 0, v[108:109]
	v_pk_mul_f32 v[110:111], v[128:129], v[114:115] op_sel_hi:[0,1]
	v_pk_mul_f32 v[114:115], v[128:129], v[106:107] op_sel_hi:[0,1]
	v_pk_mul_f32 v[106:107], v[128:129], v[104:105] op_sel_hi:[0,1]
	v_cvt_pk_bf16_f32 v104, v112, v113
	v_cvt_pk_bf16_f32 v105, v110, v111
	v_cvt_pk_bf16_f32 v106, v106, v107
	v_cvt_pk_bf16_f32 v107, v114, v115
	flat_store_dwordx4 v[108:109], v[104:107]
	v_pk_mul_f32 v[102:103], v[128:129], v[102:103] op_sel_hi:[0,1]
	v_pk_mul_f32 v[96:97], v[128:129], v[96:97] op_sel_hi:[0,1]
	v_pk_mul_f32 v[104:105], v[128:129], v[94:95] op_sel_hi:[0,1]
	v_pk_mul_f32 v[94:95], v[128:129], v[92:93] op_sel_hi:[0,1]
	v_cvt_pk_bf16_f32 v92, v100, v101
	v_cvt_pk_bf16_f32 v93, v102, v103
	v_cvt_pk_bf16_f32 v94, v94, v95
	v_cvt_pk_bf16_f32 v95, v104, v105
	flat_store_dwordx4 v[108:109], v[92:95] offset:256
	v_pk_mul_f32 v[84:85], v[128:129], v[84:85] op_sel_hi:[0,1]
	v_pk_mul_f32 v[86:87], v[128:129], v[86:87] op_sel_hi:[0,1]
	v_or_b32_e32 v92, 32, v132
	v_ashrrev_i32_e32 v93, 31, v92
	v_lshlrev_b64 v[92:93], 12, v[92:93]
	v_lshl_add_u64 v[92:93], v[130:131], 0, v[92:93]
	v_pk_mul_f32 v[94:95], v[128:129], v[98:99] op_sel_hi:[0,1]
	v_pk_mul_f32 v[98:99], v[128:129], v[90:91] op_sel_hi:[0,1]
	v_pk_mul_f32 v[90:91], v[128:129], v[88:89] op_sel_hi:[0,1]
	v_cvt_pk_bf16_f32 v88, v96, v97
	v_cvt_pk_bf16_f32 v89, v94, v95
	v_cvt_pk_bf16_f32 v90, v90, v91
	v_cvt_pk_bf16_f32 v91, v98, v99
	flat_store_dwordx4 v[92:93], v[88:91]
	v_pk_mul_f32 v[80:81], v[128:129], v[80:81] op_sel_hi:[0,1]
	v_pk_mul_f32 v[68:69], v[128:129], v[68:69] op_sel_hi:[0,1]
	v_pk_mul_f32 v[88:89], v[128:129], v[78:79] op_sel_hi:[0,1]
	v_pk_mul_f32 v[78:79], v[128:129], v[76:77] op_sel_hi:[0,1]
	v_cvt_pk_bf16_f32 v76, v84, v85
	v_cvt_pk_bf16_f32 v77, v86, v87
	v_cvt_pk_bf16_f32 v78, v78, v79
	v_cvt_pk_bf16_f32 v79, v88, v89
	flat_store_dwordx4 v[92:93], v[76:79] offset:256
	v_pk_mul_f32 v[70:71], v[128:129], v[70:71] op_sel_hi:[0,1]
	v_pk_mul_f32 v[62:63], v[128:129], v[62:63] op_sel_hi:[0,1]
	v_or_b32_e32 v76, 48, v132
	v_ashrrev_i32_e32 v77, 31, v76
	v_lshlrev_b64 v[76:77], 12, v[76:77]
	v_lshl_add_u64 v[76:77], v[130:131], 0, v[76:77]
	v_pk_mul_f32 v[78:79], v[128:129], v[82:83] op_sel_hi:[0,1]
	v_pk_mul_f32 v[82:83], v[128:129], v[74:75] op_sel_hi:[0,1]
	v_pk_mul_f32 v[74:75], v[128:129], v[72:73] op_sel_hi:[0,1]
	v_cvt_pk_bf16_f32 v72, v80, v81
	v_cvt_pk_bf16_f32 v73, v78, v79
	v_cvt_pk_bf16_f32 v74, v74, v75
	v_cvt_pk_bf16_f32 v75, v82, v83
; __device__ __forceinline__ u32x4 pack8(f32x4 a, f32x4 b) { u32x4 w; w.x = cvt_pk_bf16(a[0], a[1]); w.y = cvt_pk_bf16(a[2], a[3]); w.z = cvt_pk_bf16(b[0], b[1]); w.w = cvt_pk_bf16(b[2], b[3]); return w; }
; #define PG8_BAR __builtin_amdgcn_s_barrier()
; template <class Epi>
; __device__ __forceinline__ void gemm_phase(LAS unsigned char* lds, const Gemm g, const StaticOrder& S, const Epi& E, int wave_) {
;     ...
;         if (wr == 0) PG8_BAR;
;         E(acc, cur, wr, wc, fr, fq);
;         if (!has_next) break;
;     __device__ __forceinline__ void operator()(EP_ARGS) const {
;         const int t = u.pn >> 3; bf16_t* base = Q + (size_t)t * tstride; const float sc = t == 0 ? qscale : 1.0f; const int colt = (u.pn & 7) * 256 + wc * 32 + 8 * fq;
; #pragma unroll
;         for (int ai = 0; ai < 2; ++ai)
; #pragma unroll
;             for (int m = 0; m < 4; ++m) { const int row = EP_ROW(ai, m);
; #pragma unroll
;                 for (int bj = 0; bj < 2; ++bj) *(u32x4*)(base + (size_t)row * 2048 + colt + bj * HALF) = pack8(acc[ai][bj][m][0] * sc, acc[ai][bj][m][1] * sc); }
;     }
	flat_store_dwordx4 v[76:77], v[72:75]
	v_pk_mul_f32 v[60:61], v[128:129], v[60:61] op_sel_hi:[0,1]
	v_pk_mul_f32 v[52:53], v[128:129], v[52:53] op_sel_hi:[0,1]
	v_pk_mul_f32 v[72:73], v[128:129], v[66:67] op_sel_hi:[0,1]
	v_pk_mul_f32 v[66:67], v[128:129], v[64:65] op_sel_hi:[0,1]
	v_cvt_pk_bf16_f32 v64, v68, v69
	v_cvt_pk_bf16_f32 v65, v70, v71
	v_cvt_pk_bf16_f32 v66, v66, v67
	v_cvt_pk_bf16_f32 v67, v72, v73
	flat_store_dwordx4 v[76:77], v[64:67] offset:256
	v_pk_mul_f32 v[54:55], v[128:129], v[54:55] op_sel_hi:[0,1]
	v_pk_mul_f32 v[48:49], v[128:129], v[48:49] op_sel_hi:[0,1]
	v_add_u32_e32 v64, 0x80, v132
	v_ashrrev_i32_e32 v65, 31, v64
	v_lshlrev_b64 v[64:65], 12, v[64:65]
	v_lshl_add_u64 v[64:65], v[130:131], 0, v[64:65]
	v_pk_mul_f32 v[66:67], v[128:129], v[58:59] op_sel_hi:[0,1]
	v_pk_mul_f32 v[58:59], v[128:129], v[56:57] op_sel_hi:[0,1]
	v_cvt_pk_bf16_f32 v56, v60, v61
	v_cvt_pk_bf16_f32 v57, v62, v63
	v_cvt_pk_bf16_f32 v58, v58, v59
	v_cvt_pk_bf16_f32 v59, v66, v67
	flat_store_dwordx4 v[64:65], v[56:59]
	v_pk_mul_f32 v[36:37], v[128:129], v[36:37] op_sel_hi:[0,1]
	v_pk_mul_f32 v[38:39], v[128:129], v[38:39] op_sel_hi:[0,1]
	v_pk_mul_f32 v[56:57], v[128:129], v[46:47] op_sel_hi:[0,1]
	v_pk_mul_f32 v[46:47], v[128:129], v[44:45] op_sel_hi:[0,1]
	v_cvt_pk_bf16_f32 v44, v52, v53
	v_cvt_pk_bf16_f32 v45, v54, v55
	v_cvt_pk_bf16_f32 v46, v46, v47
	v_cvt_pk_bf16_f32 v47, v56, v57
	flat_store_dwordx4 v[64:65], v[44:47] offset:256
	v_pk_mul_f32 v[32:33], v[128:129], v[32:33] op_sel_hi:[0,1]
	v_pk_mul_f32 v[20:21], v[128:129], v[20:21] op_sel_hi:[0,1]
	v_add_u32_e32 v44, 0x90, v132
	v_ashrrev_i32_e32 v45, 31, v44
	v_lshlrev_b64 v[44:45], 12, v[44:45]
	v_lshl_add_u64 v[44:45], v[130:131], 0, v[44:45]
	v_pk_mul_f32 v[46:47], v[128:129], v[50:51] op_sel_hi:[0,1]
	v_pk_mul_f32 v[50:51], v[128:129], v[42:43] op_sel_hi:[0,1]
	v_pk_mul_f32 v[42:43], v[128:129], v[40:41] op_sel_hi:[0,1]
	v_cvt_pk_bf16_f32 v40, v48, v49
	v_cvt_pk_bf16_f32 v41, v46, v47
	v_cvt_pk_bf16_f32 v42, v42, v43
	v_cvt_pk_bf16_f32 v43, v50, v51
	flat_store_dwordx4 v[44:45], v[40:43]
	v_pk_mul_f32 v[22:23], v[128:129], v[22:23] op_sel_hi:[0,1]
	v_pk_mul_f32 v[16:17], v[128:129], v[16:17] op_sel_hi:[0,1]
	v_pk_mul_f32 v[40:41], v[128:129], v[30:31] op_sel_hi:[0,1]
	v_pk_mul_f32 v[30:31], v[128:129], v[28:29] op_sel_hi:[0,1]
	v_cvt_pk_bf16_f32 v28, v36, v37
	v_cvt_pk_bf16_f32 v29, v38, v39
	v_cvt_pk_bf16_f32 v30, v30, v31
	v_cvt_pk_bf16_f32 v31, v40, v41
	flat_store_dwordx4 v[44:45], v[28:31] offset:256
	s_andn2_b64 vcc, exec, s[40:41]
	s_mov_b64 s[12:13], -1
	v_add_u32_e32 v28, 0xa0, v132
	v_ashrrev_i32_e32 v29, 31, v28
	v_lshlrev_b64 v[28:29], 12, v[28:29]
	v_lshl_add_u64 v[28:29], v[130:131], 0, v[28:29]
	v_pk_mul_f32 v[30:31], v[128:129], v[34:35] op_sel_hi:[0,1]
	v_pk_mul_f32 v[34:35], v[128:129], v[26:27] op_sel_hi:[0,1]
	v_pk_mul_f32 v[26:27], v[128:129], v[24:25] op_sel_hi:[0,1]
	v_cvt_pk_bf16_f32 v24, v32, v33
	v_cvt_pk_bf16_f32 v25, v30, v31
	v_cvt_pk_bf16_f32 v26, v26, v27
	v_cvt_pk_bf16_f32 v27, v34, v35
	flat_store_dwordx4 v[28:29], v[24:27]
	v_pk_mul_f32 v[6:7], v[128:129], v[6:7] op_sel_hi:[0,1]
	v_pk_mul_f32 v[4:5], v[128:129], v[4:5] op_sel_hi:[0,1]
	v_pk_mul_f32 v[24:25], v[128:129], v[14:15] op_sel_hi:[0,1]
	v_pk_mul_f32 v[14:15], v[128:129], v[12:13] op_sel_hi:[0,1]
	v_cvt_pk_bf16_f32 v12, v20, v21
	v_cvt_pk_bf16_f32 v13, v22, v23
	v_cvt_pk_bf16_f32 v14, v14, v15
	v_cvt_pk_bf16_f32 v15, v24, v25
	flat_store_dwordx4 v[28:29], v[12:15] offset:256
	s_nop 1
	v_add_u32_e32 v12, 0xb0, v132
	v_ashrrev_i32_e32 v13, 31, v12
	v_lshlrev_b64 v[12:13], 12, v[12:13]
	v_lshl_add_u64 v[12:13], v[130:131], 0, v[12:13]
	v_pk_mul_f32 v[14:15], v[128:129], v[18:19] op_sel_hi:[0,1]
	v_pk_mul_f32 v[18:19], v[128:129], v[10:11] op_sel_hi:[0,1]
	v_pk_mul_f32 v[10:11], v[128:129], v[8:9] op_sel_hi:[0,1]
	v_cvt_pk_bf16_f32 v8, v16, v17
	v_cvt_pk_bf16_f32 v9, v14, v15
	v_cvt_pk_bf16_f32 v10, v10, v11
	v_cvt_pk_bf16_f32 v11, v18, v19
	flat_store_dwordx4 v[12:13], v[8:11]
	s_nop 1
	v_pk_mul_f32 v[8:9], v[128:129], v[2:3] op_sel_hi:[0,1]
	v_pk_mul_f32 v[2:3], v[128:129], v[0:1] op_sel_hi:[0,1]
	v_cvt_pk_bf16_f32 v0, v4, v5
	v_cvt_pk_bf16_f32 v1, v6, v7
	v_cvt_pk_bf16_f32 v2, v2, v3
	v_cvt_pk_bf16_f32 v3, v8, v9
	flat_store_dwordx4 v[12:13], v[0:3] offset:256
	s_setprio 0
	s_cbranch_vccnz .LBB0_187
	s_and_b64 vcc, exec, s[38:39]
	s_cbranch_vccnz .LBB0_186
	s_barrier
	s_branch .LBB0_186

; #define PG8_BAR __builtin_amdgcn_s_barrier()
; template <class Epi>
; __device__ __forceinline__ void gemm_phase(LAS unsigned char* lds, const Gemm g, const StaticOrder& S, const Epi& E, int wave_) {
;     ...
;         if (wr == 0) PG8_BAR;
;         E(acc, cur, wr, wc, fr, fq);
;         if (!has_next) break;
.LBB0_580:
	s_andn2_b64 vcc, exec, s[42:43]
	s_mov_b64 s[12:13], -1
	s_setprio 0
	s_cbranch_vccnz .LBB0_570
	s_branch .LBB0_599

; #define PG8_BAR __builtin_amdgcn_s_barrier()
; template <class Epi>
; __device__ __forceinline__ void gemm_phase(LAS unsigned char* lds, const Gemm g, const StaticOrder& S, const Epi& E, int wave_) {
;     ...
;         if (wr == 0) PG8_BAR;
;         E(acc, cur, wr, wc, fr, fq);
;         if (!has_next) break;
.LBB0_777:
	s_andn2_b64 vcc, exec, s[40:41]
	s_mov_b64 s[12:13], -1
	s_setprio 0
	s_cbranch_vccnz .LBB0_740
	s_branch .LBB0_780

; __device__ __forceinline__ u32x4 pack8(f32x4 a, f32x4 b) { u32x4 w; w.x = cvt_pk_bf16(a[0], a[1]); w.y = cvt_pk_bf16(a[2], a[3]); w.z = cvt_pk_bf16(b[0], b[1]); w.w = cvt_pk_bf16(b[2], b[3]); return w; }
;     __device__ __forceinline__ void operator()(EP_ARGS) const {
;         i64 sq[2][4];
; #pragma unroll
;         for (int ai = 0; ai < 2; ++ai)
; #pragma unroll
;             for (int m = 0; m < 4; ++m) sq[ai][m] = ssq[2 * (size_t)EP_ROW(ai, m) + 1];
;         __builtin_amdgcn_sched_barrier(0);
; #pragma unroll
;         for (int ai = 0; ai < 2; ++ai)
; #pragma unroll
;             for (int m = 0; m < 4; ++m) { const int row = EP_ROW(ai, m); const float rk = rsqrtf((float)sq[ai][m] * (1.0f / (FX_SUM * MLA_RANK)) + 1e-6f);
;                 const size_t o = (size_t)row * 2048 + u.pn * 128 + wc * 32 + 8 * fq;
;                 *(u32x4*)(KN + o) = pack8(acc[ai][0][m][0] * rk, acc[ai][0][m][1] * rk); *(u32x4*)(V + o) = pack8(acc[ai][1][m][0] * rk, acc[ai][1][m][1] * rk); }
;     }
.LBB0_799:
	v_lshl_add_u32 v162, s49, 8, v159
	v_or_b32_e32 v148, 48, v162
	v_ashrrev_i32_e32 v163, 31, v162
	v_or_b32_e32 v164, 16, v162
	v_or_b32_e32 v152, 32, v162
	v_ashrrev_i32_e32 v149, 31, v148
	v_lshl_add_u64 v[130:131], v[162:163], 4, s[8:9]
	v_ashrrev_i32_e32 v165, 31, v164
	v_ashrrev_i32_e32 v153, 31, v152
	v_lshl_add_u64 v[136:137], v[148:149], 4, s[8:9]
	v_lshl_add_u64 v[132:133], v[164:165], 4, s[8:9]
	v_lshl_add_u64 v[134:135], v[152:153], 4, s[8:9]
	flat_load_dwordx2 v[166:167], v[130:131] offset:8
	flat_load_dwordx2 v[168:169], v[132:133] offset:8
	flat_load_dwordx2 v[154:155], v[134:135] offset:8
	flat_load_dwordx2 v[150:151], v[136:137] offset:8
	v_add_u32_e32 v144, 0x80, v162
	v_add_u32_e32 v140, 0x90, v162
	v_add_u32_e32 v136, 0xa0, v162
	v_ashrrev_i32_e32 v145, 31, v144
	v_ashrrev_i32_e32 v141, 31, v140
	v_ashrrev_i32_e32 v137, 31, v136
	v_add_u32_e32 v130, 0xb0, v162
	v_lshl_add_u64 v[132:133], v[144:145], 4, s[8:9]
	v_lshl_add_u64 v[134:135], v[140:141], 4, s[8:9]
	v_lshl_add_u64 v[138:139], v[136:137], 4, s[8:9]
	v_ashrrev_i32_e32 v131, 31, v130
	v_lshl_add_u64 v[170:171], v[130:131], 4, s[8:9]
	flat_load_dwordx2 v[146:147], v[132:133] offset:8
	flat_load_dwordx2 v[142:143], v[134:135] offset:8
	s_nop 0
	flat_load_dwordx2 v[138:139], v[138:139] offset:8
	s_nop 0
	flat_load_dwordx2 v[134:135], v[170:171] offset:8
	s_waitcnt vmcnt(0) lgkmcnt(0)
	v_xor_b32_e32 v170, v166, v167
	v_ashrrev_i32_e32 v170, 31, v170
	v_ffbh_i32_e32 v171, v167
	v_add_u32_e32 v170, 32, v170
	v_add_u32_e32 v171, -1, v171
	v_min_u32_e32 v170, v171, v170
	v_lshlrev_b64 v[166:167], v170, v[166:167]
	v_min_u32_e32 v166, 1, v166
	v_or_b32_e32 v166, v167, v166
	v_cvt_f32_i32_e32 v166, v166
	v_sub_u32_e32 v167, 32, v170
	s_lshl_b32 s11, s48, 7
	s_ashr_i32 s12, s11, 31
	v_ldexp_f32 v166, v166, v167
	v_or_b32_e32 v132, s11, v128
	v_fmamk_f32 v166, v166, 0x2f000000, v225
	s_mov_b32 s11, 0x800000
	v_cmp_gt_f32_e32 vcc, s11, v166
	v_mul_f32_e32 v167, 0x4b800000, v166
	v_mov_b32_e32 v133, s12
	v_cndmask_b32_e32 v166, v166, v167, vcc
	v_rsq_f32_e32 v166, v166
	v_lshlrev_b64 v[162:163], 11, v[162:163]
	v_lshl_add_u64 v[162:163], v[162:163], 0, v[132:133]
	s_mov_b64 s[12:13], -1
	v_mul_f32_e32 v167, 0x45800000, v166
	v_cndmask_b32_e32 v166, v166, v167, vcc
	v_pk_mul_f32 v[124:125], v[124:125], v[166:167] op_sel_hi:[1,0]
	v_pk_mul_f32 v[126:127], v[126:127], v[166:167] op_sel_hi:[1,0]
	v_pk_mul_f32 v[170:171], v[122:123], v[166:167] op_sel_hi:[1,0]
	v_pk_mul_f32 v[122:123], v[120:121], v[166:167] op_sel_hi:[1,0]
	v_cvt_pk_bf16_f32 v120, v124, v125
	v_lshlrev_b64 v[124:125], 1, v[162:163]
	v_cvt_pk_bf16_f32 v121, v126, v127
	v_lshl_add_u64 v[126:127], s[4:5], 0, v[124:125]
	v_pk_mul_f32 v[116:117], v[116:117], v[166:167] op_sel_hi:[1,0]
	v_cvt_pk_bf16_f32 v122, v122, v123
	v_cvt_pk_bf16_f32 v123, v170, v171
	flat_store_dwordx4 v[126:127], v[120:123]
	v_pk_mul_f32 v[118:119], v[118:119], v[166:167] op_sel_hi:[1,0]
	s_nop 0
	v_pk_mul_f32 v[120:121], v[114:115], v[166:167] op_sel_hi:[1,0]
	v_pk_mul_f32 v[114:115], v[112:113], v[166:167] op_sel_hi:[1,0]
	v_cvt_pk_bf16_f32 v112, v116, v117
	v_lshl_add_u64 v[116:117], s[6:7], 0, v[124:125]
	v_cvt_pk_bf16_f32 v113, v118, v119
	v_cvt_pk_bf16_f32 v114, v114, v115
	v_cvt_pk_bf16_f32 v115, v120, v121
	flat_store_dwordx4 v[116:117], v[112:115]
	s_nop 1
	v_xor_b32_e32 v112, v168, v169
	v_ashrrev_i32_e32 v112, 31, v112
	v_ffbh_i32_e32 v113, v169
	v_add_u32_e32 v112, 32, v112
	v_add_u32_e32 v113, -1, v113
	v_min_u32_e32 v114, v113, v112
	v_lshlrev_b64 v[112:113], v114, v[168:169]
	v_min_u32_e32 v112, 1, v112
	v_or_b32_e32 v112, v113, v112
	v_cvt_f32_i32_e32 v112, v112
	v_sub_u32_e32 v113, 32, v114
	v_lshlrev_b64 v[114:115], 11, v[164:165]
	v_lshl_add_u64 v[114:115], v[114:115], 0, v[132:133]
	v_ldexp_f32 v112, v112, v113
	v_fmamk_f32 v112, v112, 0x2f000000, v225
	v_cmp_gt_f32_e32 vcc, s11, v112
	v_mul_f32_e32 v113, 0x4b800000, v112
	s_nop 0
	v_cndmask_b32_e32 v112, v112, v113, vcc
	v_rsq_f32_e32 v112, v112
	s_nop 0
	v_mul_f32_e32 v113, 0x45800000, v112
	v_cndmask_b32_e32 v112, v112, v113, vcc
	v_pk_mul_f32 v[108:109], v[108:109], v[112:113] op_sel_hi:[1,0]
	v_pk_mul_f32 v[110:111], v[110:111], v[112:113] op_sel_hi:[1,0]
	v_pk_mul_f32 v[116:117], v[106:107], v[112:113] op_sel_hi:[1,0]
	v_pk_mul_f32 v[106:107], v[104:105], v[112:113] op_sel_hi:[1,0]
	v_cvt_pk_bf16_f32 v104, v108, v109
	v_lshlrev_b64 v[108:109], 1, v[114:115]
	v_cvt_pk_bf16_f32 v105, v110, v111
	v_lshl_add_u64 v[110:111], s[4:5], 0, v[108:109]
	v_pk_mul_f32 v[100:101], v[100:101], v[112:113] op_sel_hi:[1,0]
	v_cvt_pk_bf16_f32 v106, v106, v107
	v_cvt_pk_bf16_f32 v107, v116, v117
	flat_store_dwordx4 v[110:111], v[104:107]
	v_pk_mul_f32 v[102:103], v[102:103], v[112:113] op_sel_hi:[1,0]
	s_nop 0
	v_pk_mul_f32 v[104:105], v[98:99], v[112:113] op_sel_hi:[1,0]
	v_pk_mul_f32 v[98:99], v[96:97], v[112:113] op_sel_hi:[1,0]
	v_cvt_pk_bf16_f32 v96, v100, v101
	v_lshl_add_u64 v[100:101], s[6:7], 0, v[108:109]
	v_cvt_pk_bf16_f32 v97, v102, v103
	v_cvt_pk_bf16_f32 v98, v98, v99
	v_cvt_pk_bf16_f32 v99, v104, v105
	flat_store_dwordx4 v[100:101], v[96:99]
	s_nop 1
	v_xor_b32_e32 v96, v154, v155
	v_ashrrev_i32_e32 v96, 31, v96
	v_ffbh_i32_e32 v97, v155
	v_add_u32_e32 v96, 32, v96
	v_add_u32_e32 v97, -1, v97
	v_min_u32_e32 v98, v97, v96
	v_lshlrev_b64 v[96:97], v98, v[154:155]
	v_min_u32_e32 v96, 1, v96
	v_or_b32_e32 v96, v97, v96
	v_cvt_f32_i32_e32 v96, v96
	v_sub_u32_e32 v97, 32, v98
	v_lshlrev_b64 v[98:99], 11, v[152:153]
	v_lshl_add_u64 v[98:99], v[98:99], 0, v[132:133]
	v_ldexp_f32 v96, v96, v97
	v_fmamk_f32 v96, v96, 0x2f000000, v225
	v_cmp_gt_f32_e32 vcc, s11, v96
; __device__ __forceinline__ u32x4 pack8(f32x4 a, f32x4 b) { u32x4 w; w.x = cvt_pk_bf16(a[0], a[1]); w.y = cvt_pk_bf16(a[2], a[3]); w.z = cvt_pk_bf16(b[0], b[1]); w.w = cvt_pk_bf16(b[2], b[3]); return w; }
;     __device__ __forceinline__ void operator()(EP_ARGS) const {
;     ...
;             for (int m = 0; m < 4; ++m) { const int row = EP_ROW(ai, m); const float rk = rsqrtf((float)sq[ai][m] * (1.0f / (FX_SUM * MLA_RANK)) + 1e-6f);
;                 const size_t o = (size_t)row * 2048 + u.pn * 128 + wc * 32 + 8 * fq;
;                 *(u32x4*)(KN + o) = pack8(acc[ai][0][m][0] * rk, acc[ai][0][m][1] * rk); *(u32x4*)(V + o) = pack8(acc[ai][1][m][0] * rk, acc[ai][1][m][1] * rk); }
	v_mul_f32_e32 v97, 0x4b800000, v96
	s_nop 0
	v_cndmask_b32_e32 v96, v96, v97, vcc
	v_rsq_f32_e32 v96, v96
	s_nop 0
	v_mul_f32_e32 v97, 0x45800000, v96
	v_cndmask_b32_e32 v96, v96, v97, vcc
	v_pk_mul_f32 v[92:93], v[92:93], v[96:97] op_sel_hi:[1,0]
	v_pk_mul_f32 v[94:95], v[94:95], v[96:97] op_sel_hi:[1,0]
	v_pk_mul_f32 v[100:101], v[90:91], v[96:97] op_sel_hi:[1,0]
	v_pk_mul_f32 v[90:91], v[88:89], v[96:97] op_sel_hi:[1,0]
	v_cvt_pk_bf16_f32 v88, v92, v93
	v_lshlrev_b64 v[92:93], 1, v[98:99]
	v_cvt_pk_bf16_f32 v89, v94, v95
	v_lshl_add_u64 v[94:95], s[4:5], 0, v[92:93]
	v_pk_mul_f32 v[84:85], v[84:85], v[96:97] op_sel_hi:[1,0]
	v_cvt_pk_bf16_f32 v90, v90, v91
	v_cvt_pk_bf16_f32 v91, v100, v101
	flat_store_dwordx4 v[94:95], v[88:91]
	v_pk_mul_f32 v[86:87], v[86:87], v[96:97] op_sel_hi:[1,0]
	s_nop 0
	v_pk_mul_f32 v[88:89], v[82:83], v[96:97] op_sel_hi:[1,0]
	v_pk_mul_f32 v[82:83], v[80:81], v[96:97] op_sel_hi:[1,0]
	v_cvt_pk_bf16_f32 v80, v84, v85
	v_lshl_add_u64 v[84:85], s[6:7], 0, v[92:93]
	v_cvt_pk_bf16_f32 v81, v86, v87
	v_cvt_pk_bf16_f32 v82, v82, v83
	v_cvt_pk_bf16_f32 v83, v88, v89
	flat_store_dwordx4 v[84:85], v[80:83]
	s_nop 1
	v_xor_b32_e32 v80, v150, v151
	v_ashrrev_i32_e32 v80, 31, v80
	v_ffbh_i32_e32 v81, v151
	v_add_u32_e32 v80, 32, v80
	v_add_u32_e32 v81, -1, v81
	v_min_u32_e32 v82, v81, v80
	v_lshlrev_b64 v[80:81], v82, v[150:151]
	v_min_u32_e32 v80, 1, v80
	v_or_b32_e32 v80, v81, v80
	v_cvt_f32_i32_e32 v80, v80
	v_sub_u32_e32 v81, 32, v82
	v_lshlrev_b64 v[82:83], 11, v[148:149]
	v_lshl_add_u64 v[82:83], v[82:83], 0, v[132:133]
	v_ldexp_f32 v80, v80, v81
	v_fmamk_f32 v80, v80, 0x2f000000, v225
	v_cmp_gt_f32_e32 vcc, s11, v80
	v_mul_f32_e32 v81, 0x4b800000, v80
	s_nop 0
	v_cndmask_b32_e32 v80, v80, v81, vcc
	v_rsq_f32_e32 v80, v80
	s_nop 0
	v_mul_f32_e32 v81, 0x45800000, v80
	v_cndmask_b32_e32 v80, v80, v81, vcc
	v_pk_mul_f32 v[76:77], v[76:77], v[80:81] op_sel_hi:[1,0]
	v_pk_mul_f32 v[78:79], v[78:79], v[80:81] op_sel_hi:[1,0]
	v_pk_mul_f32 v[84:85], v[74:75], v[80:81] op_sel_hi:[1,0]
	v_pk_mul_f32 v[74:75], v[72:73], v[80:81] op_sel_hi:[1,0]
	v_cvt_pk_bf16_f32 v72, v76, v77
	v_lshlrev_b64 v[76:77], 1, v[82:83]
	v_cvt_pk_bf16_f32 v73, v78, v79
	v_lshl_add_u64 v[78:79], s[4:5], 0, v[76:77]
	v_pk_mul_f32 v[68:69], v[68:69], v[80:81] op_sel_hi:[1,0]
	v_cvt_pk_bf16_f32 v74, v74, v75
	v_cvt_pk_bf16_f32 v75, v84, v85
	flat_store_dwordx4 v[78:79], v[72:75]
	v_pk_mul_f32 v[70:71], v[70:71], v[80:81] op_sel_hi:[1,0]
	s_nop 0
	v_pk_mul_f32 v[72:73], v[66:67], v[80:81] op_sel_hi:[1,0]
	v_pk_mul_f32 v[66:67], v[64:65], v[80:81] op_sel_hi:[1,0]
	v_cvt_pk_bf16_f32 v64, v68, v69
	v_lshl_add_u64 v[68:69], s[6:7], 0, v[76:77]
	v_cvt_pk_bf16_f32 v65, v70, v71
	v_cvt_pk_bf16_f32 v66, v66, v67
	v_cvt_pk_bf16_f32 v67, v72, v73
	flat_store_dwordx4 v[68:69], v[64:67]
	s_nop 1
	v_xor_b32_e32 v64, v146, v147
	v_ashrrev_i32_e32 v64, 31, v64
	v_ffbh_i32_e32 v65, v147
	v_add_u32_e32 v64, 32, v64
	v_add_u32_e32 v65, -1, v65
	v_min_u32_e32 v66, v65, v64
	v_lshlrev_b64 v[64:65], v66, v[146:147]
	v_min_u32_e32 v64, 1, v64
	v_or_b32_e32 v64, v65, v64
	v_cvt_f32_i32_e32 v64, v64
	v_sub_u32_e32 v65, 32, v66
	v_lshlrev_b64 v[66:67], 11, v[144:145]
	v_lshl_add_u64 v[66:67], v[66:67], 0, v[132:133]
	v_ldexp_f32 v64, v64, v65
	v_fmamk_f32 v64, v64, 0x2f000000, v225
	v_cmp_gt_f32_e32 vcc, s11, v64
	v_mul_f32_e32 v65, 0x4b800000, v64
	s_nop 0
	v_cndmask_b32_e32 v64, v64, v65, vcc
	v_rsq_f32_e32 v64, v64
	s_nop 0
	v_mul_f32_e32 v65, 0x45800000, v64
	v_cndmask_b32_e32 v64, v64, v65, vcc
	v_pk_mul_f32 v[60:61], v[60:61], v[64:65] op_sel_hi:[1,0]
	v_pk_mul_f32 v[62:63], v[62:63], v[64:65] op_sel_hi:[1,0]
	v_pk_mul_f32 v[68:69], v[58:59], v[64:65] op_sel_hi:[1,0]
	v_pk_mul_f32 v[58:59], v[56:57], v[64:65] op_sel_hi:[1,0]
	v_cvt_pk_bf16_f32 v56, v60, v61
	v_lshlrev_b64 v[60:61], 1, v[66:67]
	v_cvt_pk_bf16_f32 v57, v62, v63
	v_lshl_add_u64 v[62:63], s[4:5], 0, v[60:61]
	v_pk_mul_f32 v[52:53], v[52:53], v[64:65] op_sel_hi:[1,0]
	v_cvt_pk_bf16_f32 v58, v58, v59
	v_cvt_pk_bf16_f32 v59, v68, v69
	flat_store_dwordx4 v[62:63], v[56:59]
	v_pk_mul_f32 v[54:55], v[54:55], v[64:65] op_sel_hi:[1,0]
	s_nop 0
	v_pk_mul_f32 v[56:57], v[50:51], v[64:65] op_sel_hi:[1,0]
	v_pk_mul_f32 v[50:51], v[48:49], v[64:65] op_sel_hi:[1,0]
	v_cvt_pk_bf16_f32 v48, v52, v53
	v_lshl_add_u64 v[52:53], s[6:7], 0, v[60:61]
	v_cvt_pk_bf16_f32 v49, v54, v55
	v_cvt_pk_bf16_f32 v50, v50, v51
	v_cvt_pk_bf16_f32 v51, v56, v57
	flat_store_dwordx4 v[52:53], v[48:51]
	s_nop 1
	v_xor_b32_e32 v48, v142, v143
	v_ashrrev_i32_e32 v48, 31, v48
	v_ffbh_i32_e32 v49, v143
	v_add_u32_e32 v48, 32, v48
	v_add_u32_e32 v49, -1, v49
	v_min_u32_e32 v50, v49, v48
	v_lshlrev_b64 v[48:49], v50, v[142:143]
	v_min_u32_e32 v48, 1, v48
	v_or_b32_e32 v48, v49, v48
	v_cvt_f32_i32_e32 v48, v48
; __device__ __forceinline__ u32x4 pack8(f32x4 a, f32x4 b) { u32x4 w; w.x = cvt_pk_bf16(a[0], a[1]); w.y = cvt_pk_bf16(a[2], a[3]); w.z = cvt_pk_bf16(b[0], b[1]); w.w = cvt_pk_bf16(b[2], b[3]); return w; }
; #define PG8_BAR __builtin_amdgcn_s_barrier()
; template <class Epi>
; __device__ __forceinline__ void gemm_phase(LAS unsigned char* lds, const Gemm g, const StaticOrder& S, const Epi& E, int wave_) {
;     ...
;         if (wr == 0) PG8_BAR;
;         E(acc, cur, wr, wc, fr, fq);
;         if (!has_next) break;
; #pragma unroll
;         for (int a = 0; a < 2; ++a)
; #pragma unroll
;             for (int b = 0; b < 2; ++b)
; #pragma unroll
;                 for (int m = 0; m < 4; ++m)
; #pragma unroll
;                     for (int n = 0; n < 2; ++n) acc[a][b][m][n] = (f32x4){0.f, 0.f, 0.f, 0.f};
;         cur = nxt; cA = nA; cB = nB; ++ui;
;         if (wr == 1) PG8_BAR;
;     __device__ __forceinline__ void operator()(EP_ARGS) const {
;     ...
;         for (int ai = 0; ai < 2; ++ai)
; #pragma unroll
;             for (int m = 0; m < 4; ++m) { const int row = EP_ROW(ai, m); const float rk = rsqrtf((float)sq[ai][m] * (1.0f / (FX_SUM * MLA_RANK)) + 1e-6f);
;                 const size_t o = (size_t)row * 2048 + u.pn * 128 + wc * 32 + 8 * fq;
;                 *(u32x4*)(KN + o) = pack8(acc[ai][0][m][0] * rk, acc[ai][0][m][1] * rk); *(u32x4*)(V + o) = pack8(acc[ai][1][m][0] * rk, acc[ai][1][m][1] * rk); }
	v_sub_u32_e32 v49, 32, v50
	v_lshlrev_b64 v[50:51], 11, v[140:141]
	v_lshl_add_u64 v[50:51], v[50:51], 0, v[132:133]
	v_ldexp_f32 v48, v48, v49
	v_fmamk_f32 v48, v48, 0x2f000000, v225
	v_cmp_gt_f32_e32 vcc, s11, v48
	v_mul_f32_e32 v49, 0x4b800000, v48
	s_nop 0
	v_cndmask_b32_e32 v48, v48, v49, vcc
	v_rsq_f32_e32 v48, v48
	s_nop 0
	v_mul_f32_e32 v49, 0x45800000, v48
	v_cndmask_b32_e32 v48, v48, v49, vcc
	v_pk_mul_f32 v[44:45], v[44:45], v[48:49] op_sel_hi:[1,0]
	v_pk_mul_f32 v[46:47], v[46:47], v[48:49] op_sel_hi:[1,0]
	v_pk_mul_f32 v[52:53], v[42:43], v[48:49] op_sel_hi:[1,0]
	v_pk_mul_f32 v[42:43], v[40:41], v[48:49] op_sel_hi:[1,0]
	v_cvt_pk_bf16_f32 v40, v44, v45
	v_lshlrev_b64 v[44:45], 1, v[50:51]
	v_cvt_pk_bf16_f32 v41, v46, v47
	v_lshl_add_u64 v[46:47], s[4:5], 0, v[44:45]
	v_pk_mul_f32 v[36:37], v[36:37], v[48:49] op_sel_hi:[1,0]
	v_cvt_pk_bf16_f32 v42, v42, v43
	v_cvt_pk_bf16_f32 v43, v52, v53
	flat_store_dwordx4 v[46:47], v[40:43]
	v_pk_mul_f32 v[38:39], v[38:39], v[48:49] op_sel_hi:[1,0]
	s_nop 0
	v_pk_mul_f32 v[40:41], v[34:35], v[48:49] op_sel_hi:[1,0]
	v_pk_mul_f32 v[34:35], v[32:33], v[48:49] op_sel_hi:[1,0]
	v_cvt_pk_bf16_f32 v32, v36, v37
	v_lshl_add_u64 v[36:37], s[6:7], 0, v[44:45]
	v_cvt_pk_bf16_f32 v33, v38, v39
	v_cvt_pk_bf16_f32 v34, v34, v35
	v_cvt_pk_bf16_f32 v35, v40, v41
	flat_store_dwordx4 v[36:37], v[32:35]
	s_nop 1
	v_xor_b32_e32 v32, v138, v139
	v_ashrrev_i32_e32 v32, 31, v32
	v_ffbh_i32_e32 v33, v139
	v_add_u32_e32 v32, 32, v32
	v_add_u32_e32 v33, -1, v33
	v_min_u32_e32 v34, v33, v32
	v_lshlrev_b64 v[32:33], v34, v[138:139]
	v_min_u32_e32 v32, 1, v32
	v_or_b32_e32 v32, v33, v32
	v_cvt_f32_i32_e32 v32, v32
	v_sub_u32_e32 v33, 32, v34
	v_lshlrev_b64 v[34:35], 11, v[136:137]
	v_lshl_add_u64 v[34:35], v[34:35], 0, v[132:133]
	v_ldexp_f32 v32, v32, v33
	v_fmamk_f32 v32, v32, 0x2f000000, v225
	v_cmp_gt_f32_e32 vcc, s11, v32
	v_mul_f32_e32 v33, 0x4b800000, v32
	s_nop 0
	v_cndmask_b32_e32 v32, v32, v33, vcc
	v_rsq_f32_e32 v32, v32
	s_nop 0
	v_mul_f32_e32 v33, 0x45800000, v32
	v_cndmask_b32_e32 v32, v32, v33, vcc
	v_pk_mul_f32 v[28:29], v[28:29], v[32:33] op_sel_hi:[1,0]
	v_pk_mul_f32 v[30:31], v[30:31], v[32:33] op_sel_hi:[1,0]
	v_pk_mul_f32 v[36:37], v[26:27], v[32:33] op_sel_hi:[1,0]
	v_pk_mul_f32 v[26:27], v[24:25], v[32:33] op_sel_hi:[1,0]
	v_cvt_pk_bf16_f32 v24, v28, v29
	v_lshlrev_b64 v[28:29], 1, v[34:35]
	v_cvt_pk_bf16_f32 v25, v30, v31
	v_lshl_add_u64 v[30:31], s[4:5], 0, v[28:29]
	v_pk_mul_f32 v[20:21], v[20:21], v[32:33] op_sel_hi:[1,0]
	v_cvt_pk_bf16_f32 v26, v26, v27
	v_cvt_pk_bf16_f32 v27, v36, v37
	flat_store_dwordx4 v[30:31], v[24:27]
	v_pk_mul_f32 v[22:23], v[22:23], v[32:33] op_sel_hi:[1,0]
	s_nop 0
	v_pk_mul_f32 v[24:25], v[18:19], v[32:33] op_sel_hi:[1,0]
	v_pk_mul_f32 v[18:19], v[16:17], v[32:33] op_sel_hi:[1,0]
	v_cvt_pk_bf16_f32 v16, v20, v21
	v_lshl_add_u64 v[20:21], s[6:7], 0, v[28:29]
	v_cvt_pk_bf16_f32 v17, v22, v23
	v_cvt_pk_bf16_f32 v18, v18, v19
	v_cvt_pk_bf16_f32 v19, v24, v25
	flat_store_dwordx4 v[20:21], v[16:19]
	s_nop 1
	v_xor_b32_e32 v16, v134, v135
	v_ashrrev_i32_e32 v16, 31, v16
	v_ffbh_i32_e32 v17, v135
	v_add_u32_e32 v16, 32, v16
	v_add_u32_e32 v17, -1, v17
	v_min_u32_e32 v18, v17, v16
	v_lshlrev_b64 v[16:17], v18, v[134:135]
	v_min_u32_e32 v16, 1, v16
	v_or_b32_e32 v16, v17, v16
	v_cvt_f32_i32_e32 v16, v16
	v_sub_u32_e32 v17, 32, v18
	v_lshlrev_b64 v[18:19], 11, v[130:131]
	v_lshl_add_u64 v[18:19], v[18:19], 0, v[132:133]
	v_ldexp_f32 v16, v16, v17
	v_fmamk_f32 v16, v16, 0x2f000000, v225
	v_cmp_gt_f32_e32 vcc, s11, v16
	v_mul_f32_e32 v17, 0x4b800000, v16
	s_nop 0
	v_cndmask_b32_e32 v16, v16, v17, vcc
	v_rsq_f32_e32 v16, v16
	s_nop 0
	v_mul_f32_e32 v17, 0x45800000, v16
	v_cndmask_b32_e32 v16, v16, v17, vcc
	v_pk_mul_f32 v[12:13], v[12:13], v[16:17] op_sel_hi:[1,0]
	v_pk_mul_f32 v[14:15], v[14:15], v[16:17] op_sel_hi:[1,0]
	v_pk_mul_f32 v[20:21], v[10:11], v[16:17] op_sel_hi:[1,0]
	v_pk_mul_f32 v[10:11], v[8:9], v[16:17] op_sel_hi:[1,0]
	v_cvt_pk_bf16_f32 v8, v12, v13
	v_lshlrev_b64 v[12:13], 1, v[18:19]
	v_cvt_pk_bf16_f32 v9, v14, v15
	v_lshl_add_u64 v[14:15], s[4:5], 0, v[12:13]
	v_pk_mul_f32 v[4:5], v[4:5], v[16:17] op_sel_hi:[1,0]
	v_cvt_pk_bf16_f32 v10, v10, v11
	v_cvt_pk_bf16_f32 v11, v20, v21
	flat_store_dwordx4 v[14:15], v[8:11]
	s_andn2_b64 vcc, exec, s[40:41]
	v_pk_mul_f32 v[6:7], v[6:7], v[16:17] op_sel_hi:[1,0]
	v_pk_mul_f32 v[8:9], v[2:3], v[16:17] op_sel_hi:[1,0]
	v_pk_mul_f32 v[2:3], v[0:1], v[16:17] op_sel_hi:[1,0]
	v_cvt_pk_bf16_f32 v0, v4, v5
	v_lshl_add_u64 v[4:5], s[6:7], 0, v[12:13]
	v_cvt_pk_bf16_f32 v1, v6, v7
	v_cvt_pk_bf16_f32 v2, v2, v3
	v_cvt_pk_bf16_f32 v3, v8, v9
	flat_store_dwordx4 v[4:5], v[0:3]
	s_setprio 0
	s_cbranch_vccnz .LBB0_788
	s_and_b64 vcc, exec, s[38:39]
	s_cbranch_vccnz .LBB0_787
	s_barrier
	s_branch .LBB0_787

; #define PG8_BAR __builtin_amdgcn_s_barrier()
; __device__ __forceinline__ float fq_sum(float s) { return x16x32_sum(s); }
; template <class Epi>
; __device__ __forceinline__ void gemm_phase(LAS unsigned char* lds, const Gemm g, const StaticOrder& S, const Epi& E, int wave_) {
;     ...
;         if (wr == 0) PG8_BAR;
;         E(acc, cur, wr, wc, fr, fq);
;         if (!has_next) break;
; #pragma unroll
;         for (int a = 0; a < 2; ++a)
; #pragma unroll
;             for (int b = 0; b < 2; ++b)
; #pragma unroll
;                 for (int m = 0; m < 4; ++m)
; #pragma unroll
;                     for (int n = 0; n < 2; ++n) acc[a][b][m][n] = (f32x4){0.f, 0.f, 0.f, 0.f};
;         cur = nxt; cA = nA; cB = nB; ++ui;
;         if (wr == 1) PG8_BAR;
;     __device__ __forceinline__ void operator()(EP_ARGS) const {
;     ...
;                 s = fq_sum(s); q = fq_sum(q);
;                 if (fq == 0) atomic_add_stat(stats + (size_t)row, s, q); }
;             asm volatile("" ::: "memory"); }
.LBB0_1123:
	s_or_b64 exec, exec, s[12:13]
	s_andn2_b64 vcc, exec, s[44:45]
	s_mov_b64 s[12:13], -1
	s_setprio 0
	s_cbranch_vccnz .LBB0_1096
	s_and_b64 vcc, exec, s[38:39]
	s_cbranch_vccnz .LBB0_1095
	s_barrier
	s_branch .LBB0_1095

; __device__ __forceinline__ u32x4 pack8(f32x4 a, f32x4 b) { u32x4 w; w.x = cvt_pk_bf16(a[0], a[1]); w.y = cvt_pk_bf16(a[2], a[3]); w.z = cvt_pk_bf16(b[0], b[1]); w.w = cvt_pk_bf16(b[2], b[3]); return w; }
;     __device__ __forceinline__ void operator()(EP_ARGS) const {
;         f32x4 cv[2][2], wv[2][2];
; #pragma unroll
;         for (int bj = 0; bj < 2; ++bj)
; #pragma unroll
;             for (int n = 0; n < 2; ++n) { cv[bj][n] = *(const f32x4*)(cs + EP_COL8(bj) + 4 * n); wv[bj][n] = *(const f32x4*)(bw + EP_COL8(bj) + 4 * n); }
;         i64 tq[2][4];
; #pragma unroll
;         for (int ai = 0; ai < 2; ++ai)
; #pragma unroll
;             for (int m = 0; m < 4; ++m) tq[ai][m] = st[(size_t)EP_ROW(ai, m)];
;         __builtin_amdgcn_sched_barrier(0);
; #pragma unroll
;         for (int ai = 0; ai < 2; ++ai)
; #pragma unroll
;             for (int m = 0; m < 4; ++m) { const int row = EP_ROW(ai, m); float mu, rstd; ln_unpack(tq[ai][m], mu, rstd); f32x4 h[2];
; #pragma unroll
;                 for (int n = 0; n < 2; ++n) { const float m2 = -mu * rstd;
;                     const f32x4 gg = ln_fold4(acc[ai][0][m][n], cv[0][n], wv[0][n], m2, rstd), uu = ln_fold4(acc[ai][1][m][n], cv[1][n], wv[1][n], m2, rstd);
;                     h[n] = silu_mul4(gg, uu); }
;                 *(u32x4*)(HF + (size_t)row * DFF + u.pn * 128 + wc * 32 + 8 * fq) = pack8(h[0], h[1]); }
.LBB0_1325:
	v_lshl_or_b32 v128, s52, 8, v179
	v_ashrrev_i32_e32 v129, 31, v128
	v_lshlrev_b64 v[130:131], 2, v[128:129]
	v_or_b32_e32 v128, 0x80, v128
	v_lshl_add_u32 v190, s54, 8, v176
	v_ashrrev_i32_e32 v129, 31, v128
	v_ashrrev_i32_e32 v191, 31, v190
	v_lshl_add_u64 v[132:133], s[8:9], 0, v[130:131]
	v_lshl_add_u64 v[130:131], s[10:11], 0, v[130:131]
	v_lshl_add_u64 v[134:135], v[128:129], 2, s[10:11]
	v_lshl_add_u64 v[160:161], v[190:191], 3, s[6:7]
	flat_load_dwordx4 v[152:155], v[132:133]
	flat_load_dwordx4 v[136:139], v[132:133] offset:16
	flat_load_dwordx4 v[156:159], v[130:131]
	flat_load_dwordx4 v[140:143], v[130:131] offset:16
	flat_load_dwordx4 v[144:147], v[132:133] offset:512
	s_nop 0
	flat_load_dwordx4 v[128:131], v[132:133] offset:528
	flat_load_dwordx4 v[148:151], v[134:135]
	s_nop 0
	flat_load_dwordx4 v[132:135], v[134:135] offset:16
	s_nop 0
	flat_load_dwordx2 v[192:193], v[160:161]
	flat_load_dwordx2 v[194:195], v[160:161] offset:128
	flat_load_dwordx2 v[196:197], v[160:161] offset:256
	flat_load_dwordx2 v[168:169], v[160:161] offset:384
	flat_load_dwordx2 v[166:167], v[160:161] offset:1024
	flat_load_dwordx2 v[164:165], v[160:161] offset:1152
	flat_load_dwordx2 v[162:163], v[160:161] offset:1280
	s_nop 0
	flat_load_dwordx2 v[160:161], v[160:161] offset:1408
	v_or_b32_e32 v183, 16, v190
	v_or_b32_e32 v191, 32, v190
	v_or_b32_e32 v198, 48, v190
	v_add_u32_e32 v199, 0x80, v190
	v_add_u32_e32 v182, 0x90, v190
	v_add_u32_e32 v181, 0xa0, v190
	v_add_u32_e32 v180, 0xb0, v190
	s_waitcnt vmcnt(0) lgkmcnt(0)
	v_cvt_f32_i32_e32 v193, v193
	v_cvt_f32_u32_e32 v192, v192
	s_mov_b32 s36, 0x35000000
	s_mov_b32 s37, 0x33000000
	v_mul_f32_e32 v193, 0x33000000, v193
	v_mul_f32_e32 v200, v193, v193
	v_fma_f32 v192, v192, s36, -v200
	v_max_f32_e32 v192, 0, v192
	v_add_f32_e32 v192, 0x3727c5ac, v192
	v_rsq_f32_e32 v192, v192
	s_lshl_b32 s12, s52, 7
	s_movk_i32 s19, 0x2c00
	s_ashr_i32 s13, s12, 31
	v_mul_f32_e64 v193, v192, -v193
	v_fma_f32 v200, v152, v193, v156
	v_fma_f32 v201, v153, v193, v157
	v_fma_f32 v202, v154, v193, v158
	v_fma_f32 v203, v155, v193, v159
	v_fma_f32 v200, v124, v192, v200
	v_fma_f32 v201, v125, v192, v201
	v_fma_f32 v202, v126, v192, v202
	v_fma_f32 v203, v127, v192, v203
	v_fma_f32 v124, v144, v193, v148
	v_fma_f32 v125, v145, v193, v149
	v_fma_f32 v126, v146, v193, v150
	v_fma_f32 v127, v147, v193, v151
	v_fma_f32 v124, v116, v192, v124
	v_fma_f32 v125, v117, v192, v125
	v_fma_f32 v126, v118, v192, v126
	v_fma_f32 v127, v119, v192, v127
	v_fma_f32 v116, v136, v193, v140
	v_fma_f32 v117, v137, v193, v141
	v_fma_f32 v118, v138, v193, v142
	v_fma_f32 v119, v139, v193, v143
	v_fma_f32 v116, v120, v192, v116
	v_fma_f32 v117, v121, v192, v117
	v_fma_f32 v118, v122, v192, v118
	v_fma_f32 v119, v123, v192, v119
	v_fma_f32 v120, v128, v193, v132
	v_fma_f32 v121, v129, v193, v133
	v_fma_f32 v122, v130, v193, v134
	v_fma_f32 v123, v131, v193, v135
	v_fma_f32 v120, v112, v192, v120
	v_fma_f32 v121, v113, v192, v121
	v_fma_f32 v122, v114, v192, v122
	v_fma_f32 v123, v115, v192, v123
	s_lshl_b64 s[12:13], s[12:13], 1
	v_mul_f32 v114, 0xbfb8aa3b, v200
	v_mul_f32 v193, 0xbfb8aa3b, v201
	v_mul_f32 v204, 0xbfb8aa3b, v202
	v_mul_f32 v205, 0xbfb8aa3b, v203
	v_exp_f32 v114, v114
	v_exp_f32 v193, v193
	v_exp_f32 v204, v204
	v_exp_f32 v205, v205
	v_mul_f32 v112, v200, v124
	v_mul_f32 v113, v201, v125
	v_mul_f32 v115, v202, v126
	v_mul_f32 v192, v203, v127
	v_add_f32 v114, 1.0, v114
	v_add_f32 v193, 1.0, v193
	v_add_f32 v204, 1.0, v204
	v_add_f32 v205, 1.0, v205
	v_rcp_f32 v114, v114
	v_rcp_f32 v193, v193
	v_rcp_f32 v204, v204
	v_rcp_f32 v205, v205
	s_nop 0
	v_mul_f32 v112, v112, v114
	v_mul_f32 v113, v113, v193
	v_mul_f32 v115, v115, v204
	v_mul_f32 v192, v192, v205
	s_andn2_b64 vcc, exec, s[42:43]
	v_mul_f32 v114, 0xbfb8aa3b, v116
	v_mul_f32 v193, 0xbfb8aa3b, v117
	v_mul_f32 v200, 0xbfb8aa3b, v118
	v_mul_f32 v201, 0xbfb8aa3b, v119
	v_exp_f32 v114, v114
	v_exp_f32 v193, v193
	v_exp_f32 v200, v200
	v_exp_f32 v201, v201
	v_mul_f32 v124, v116, v120
	v_mul_f32 v125, v117, v121
	v_mul_f32 v126, v118, v122
	v_mul_f32 v127, v119, v123
	v_add_f32 v114, 1.0, v114
	v_add_f32 v193, 1.0, v193
	v_add_f32 v200, 1.0, v200
	v_add_f32 v201, 1.0, v201
	v_rcp_f32 v114, v114
	v_rcp_f32 v193, v193
	v_rcp_f32 v200, v200
	v_rcp_f32 v201, v201
	s_nop 0
	v_mul_f32 v124, v124, v114
	v_mul_f32 v125, v125, v193
	v_mul_f32 v126, v126, v200
	v_mul_f32 v127, v127, v201
	v_cvt_f32_i32_e32 v120, v195
	v_cvt_f32_u32_e32 v121, v194
	v_cvt_pk_bf16_f32 v114, v112, v113
	v_mov_b64_e32 v[112:113], s[4:5]
	v_mul_f32_e32 v120, 0x33000000, v120
	v_mul_f32_e32 v122, v120, v120
	v_fma_f32 v121, v121, s36, -v122
	v_max_f32_e32 v121, 0, v121
	v_mad_i64_i32 v[118:119], s[16:17], v190, s19, v[112:113]
	v_add_f32_e32 v121, 0x3727c5ac, v121
	v_readlane_b32 s16, v253, 7
	v_rsq_f32_e32 v121, v121
	v_lshl_add_u64 v[118:119], v[118:119], 0, s[12:13]
	s_lshl_b32 s52, s16, 1
	v_lshl_add_u64 v[118:119], v[118:119], 0, s[52:53]
	v_cvt_pk_bf16_f32 v115, v115, v192
	v_cvt_pk_bf16_f32 v116, v124, v125
	v_cvt_pk_bf16_f32 v117, v126, v127
	v_lshl_add_u64 v[118:119], v[118:119], 0, v[184:185]
	flat_store_dwordx4 v[118:119], v[114:117]
	v_readlane_b32 s61, v255, 16
	v_readlane_b32 s59, v255, 18
	v_mul_f32_e64 v114, v121, -v120
	v_fma_f32 v115, v152, v114, v156
	v_fma_f32 v116, v153, v114, v157
	v_fma_f32 v117, v154, v114, v158
	v_fma_f32 v118, v155, v114, v159
	v_fma_f32 v115, v108, v121, v115
	v_fma_f32 v116, v109, v121, v116
	v_fma_f32 v117, v110, v121, v117
	v_fma_f32 v118, v111, v121, v118
	v_fma_f32 v108, v144, v114, v148
	v_fma_f32 v109, v145, v114, v149
	v_fma_f32 v110, v146, v114, v150
; __device__ __forceinline__ u32x4 pack8(f32x4 a, f32x4 b) { u32x4 w; w.x = cvt_pk_bf16(a[0], a[1]); w.y = cvt_pk_bf16(a[2], a[3]); w.z = cvt_pk_bf16(b[0], b[1]); w.w = cvt_pk_bf16(b[2], b[3]); return w; }
;     __device__ __forceinline__ void operator()(EP_ARGS) const {
;     ...
;             for (int m = 0; m < 4; ++m) { const int row = EP_ROW(ai, m); float mu, rstd; ln_unpack(tq[ai][m], mu, rstd); f32x4 h[2];
; #pragma unroll
;                 for (int n = 0; n < 2; ++n) { const float m2 = -mu * rstd;
;                     const f32x4 gg = ln_fold4(acc[ai][0][m][n], cv[0][n], wv[0][n], m2, rstd), uu = ln_fold4(acc[ai][1][m][n], cv[1][n], wv[1][n], m2, rstd);
;                     h[n] = silu_mul4(gg, uu); }
;                 *(u32x4*)(HF + (size_t)row * DFF + u.pn * 128 + wc * 32 + 8 * fq) = pack8(h[0], h[1]); }
	v_fma_f32 v111, v147, v114, v151
	v_fma_f32 v108, v100, v121, v108
	v_fma_f32 v109, v101, v121, v109
	v_fma_f32 v110, v102, v121, v110
	v_fma_f32 v111, v103, v121, v111
	v_readlane_b32 s60, v255, 19
	v_mul_f32 v119, 0xbfb8aa3b, v115
	v_mul_f32 v120, 0xbfb8aa3b, v116
	v_mul_f32 v122, 0xbfb8aa3b, v117
	v_mul_f32 v123, 0xbfb8aa3b, v118
	v_exp_f32 v119, v119
	v_exp_f32 v120, v120
	v_exp_f32 v122, v122
	v_exp_f32 v123, v123
	v_mul_f32 v100, v115, v108
	v_mul_f32 v101, v116, v109
	v_mul_f32 v102, v117, v110
	v_mul_f32 v103, v118, v111
	v_add_f32 v119, 1.0, v119
	v_add_f32 v120, 1.0, v120
	v_add_f32 v122, 1.0, v122
	v_add_f32 v123, 1.0, v123
	v_rcp_f32 v119, v119
	v_rcp_f32 v120, v120
	v_rcp_f32 v122, v122
	v_rcp_f32 v123, v123
	s_nop 0
	v_mul_f32 v100, v100, v119
	v_mul_f32 v101, v101, v120
	v_mul_f32 v102, v102, v122
	v_mul_f32 v103, v103, v123
	v_fma_f32 v108, v136, v114, v140
	v_fma_f32 v109, v137, v114, v141
	v_fma_f32 v110, v138, v114, v142
	v_fma_f32 v111, v139, v114, v143
	v_fma_f32 v108, v104, v121, v108
	v_fma_f32 v109, v105, v121, v109
	v_fma_f32 v110, v106, v121, v110
	v_fma_f32 v111, v107, v121, v111
	v_fma_f32 v104, v128, v114, v132
	v_fma_f32 v105, v129, v114, v133
	v_fma_f32 v106, v130, v114, v134
	v_fma_f32 v107, v131, v114, v135
	v_fma_f32 v104, v96, v121, v104
	v_fma_f32 v105, v97, v121, v105
	v_fma_f32 v106, v98, v121, v106
	v_fma_f32 v107, v99, v121, v107
	s_nop 0
	v_mul_f32 v96, 0xbfb8aa3b, v108
	v_mul_f32 v97, 0xbfb8aa3b, v109
	v_mul_f32 v116, 0xbfb8aa3b, v110
	v_mul_f32 v117, 0xbfb8aa3b, v111
	v_exp_f32 v96, v96
	v_exp_f32 v97, v97
	v_exp_f32 v116, v116
	v_exp_f32 v117, v117
	v_mul_f32 v98, v108, v104
	v_mul_f32 v99, v109, v105
	v_mul_f32 v114, v110, v106
	v_mul_f32 v115, v111, v107
	v_add_f32 v96, 1.0, v96
	v_add_f32 v97, 1.0, v97
	v_add_f32 v116, 1.0, v116
	v_add_f32 v117, 1.0, v117
	v_rcp_f32 v96, v96
	v_rcp_f32 v97, v97
	v_rcp_f32 v116, v116
	v_rcp_f32 v117, v117
	s_nop 0
	v_mul_f32 v98, v98, v96
	v_mul_f32 v99, v99, v97
	v_mul_f32 v114, v114, v116
	v_mul_f32 v115, v115, v117
	s_nop 0
	v_cvt_pk_bf16_f32 v96, v100, v101
	v_cvt_pk_bf16_f32 v97, v102, v103
	v_cvt_f32_i32_e32 v102, v197
	v_cvt_f32_u32_e32 v103, v196
	v_mad_i64_i32 v[100:101], s[16:17], v183, s19, v[112:113]
	v_mul_f32_e32 v102, 0x33000000, v102
	v_mul_f32_e32 v104, v102, v102
	v_fma_f32 v103, v103, s36, -v104
	v_max_f32_e32 v103, 0, v103
	v_add_f32_e32 v103, 0x3727c5ac, v103
	v_rsq_f32_e32 v103, v103
	v_lshl_add_u64 v[100:101], v[100:101], 0, s[12:13]
	v_lshl_add_u64 v[100:101], v[100:101], 0, s[52:53]
	v_cvt_pk_bf16_f32 v98, v98, v99
	v_cvt_pk_bf16_f32 v99, v114, v115
	v_lshl_add_u64 v[100:101], v[100:101], 0, v[184:185]
	flat_store_dwordx4 v[100:101], v[96:99]
	s_nop 1
	v_mul_f32_e64 v96, v103, -v102
	v_fma_f32 v97, v152, v96, v156
	v_fma_f32 v98, v153, v96, v157
	v_fma_f32 v99, v154, v96, v158
	v_fma_f32 v100, v155, v96, v159
	v_fma_f32 v97, v92, v103, v97
	v_fma_f32 v98, v93, v103, v98
	v_fma_f32 v99, v94, v103, v99
	v_fma_f32 v100, v95, v103, v100
	v_fma_f32 v92, v144, v96, v148
	v_fma_f32 v93, v145, v96, v149
	v_fma_f32 v94, v146, v96, v150
	v_fma_f32 v95, v147, v96, v151
	v_fma_f32 v92, v84, v103, v92
	v_fma_f32 v93, v85, v103, v93
	v_fma_f32 v94, v86, v103, v94
	v_fma_f32 v95, v87, v103, v95
	s_nop 0
	v_mul_f32 v101, 0xbfb8aa3b, v97
	v_mul_f32 v102, 0xbfb8aa3b, v98
	v_mul_f32 v104, 0xbfb8aa3b, v99
	v_mul_f32 v105, 0xbfb8aa3b, v100
	v_exp_f32 v101, v101
	v_exp_f32 v102, v102
	v_exp_f32 v104, v104
	v_exp_f32 v105, v105
	v_mul_f32 v84, v97, v92
	v_mul_f32 v85, v98, v93
	v_mul_f32 v86, v99, v94
	v_mul_f32 v87, v100, v95
	v_add_f32 v101, 1.0, v101
	v_add_f32 v102, 1.0, v102
	v_add_f32 v104, 1.0, v104
	v_add_f32 v105, 1.0, v105
	v_rcp_f32 v101, v101
	v_rcp_f32 v102, v102
	v_rcp_f32 v104, v104
	v_rcp_f32 v105, v105
	s_nop 0
	v_mul_f32 v84, v84, v101
	v_mul_f32 v85, v85, v102
	v_mul_f32 v86, v86, v104
	v_mul_f32 v87, v87, v105
	v_fma_f32 v92, v136, v96, v140
	v_fma_f32 v93, v137, v96, v141
	v_fma_f32 v94, v138, v96, v142
	v_fma_f32 v95, v139, v96, v143
	v_fma_f32 v92, v88, v103, v92
	v_fma_f32 v93, v89, v103, v93
	v_fma_f32 v94, v90, v103, v94
	v_fma_f32 v95, v91, v103, v95
	v_fma_f32 v88, v128, v96, v132
	v_fma_f32 v89, v129, v96, v133
	v_fma_f32 v90, v130, v96, v134
	v_fma_f32 v91, v131, v96, v135
	v_fma_f32 v88, v80, v103, v88
	v_fma_f32 v89, v81, v103, v89
	v_fma_f32 v90, v82, v103, v90
	v_fma_f32 v91, v83, v103, v91
	s_nop 0
	v_mul_f32 v80, 0xbfb8aa3b, v92
	v_mul_f32 v81, 0xbfb8aa3b, v93
	v_mul_f32 v98, 0xbfb8aa3b, v94
	v_mul_f32 v99, 0xbfb8aa3b, v95
	v_exp_f32 v80, v80
	v_exp_f32 v81, v81
	v_exp_f32 v98, v98
	v_exp_f32 v99, v99
	v_mul_f32 v82, v92, v88
	v_mul_f32 v83, v93, v89
	v_mul_f32 v96, v94, v90
	v_mul_f32 v97, v95, v91
	v_add_f32 v80, 1.0, v80
	v_add_f32 v81, 1.0, v81
	v_add_f32 v98, 1.0, v98
	v_add_f32 v99, 1.0, v99
	v_rcp_f32 v80, v80
	v_rcp_f32 v81, v81
	v_rcp_f32 v98, v98
	v_rcp_f32 v99, v99
	s_nop 0
	v_mul_f32 v82, v82, v80
	v_mul_f32 v83, v83, v81
	v_mul_f32 v96, v96, v98
	v_mul_f32 v97, v97, v99
	s_nop 0
	v_cvt_pk_bf16_f32 v80, v84, v85
	v_cvt_pk_bf16_f32 v81, v86, v87
	v_cvt_f32_i32_e32 v86, v169
	v_cvt_f32_u32_e32 v87, v168
	v_mad_i64_i32 v[84:85], s[16:17], v191, s19, v[112:113]
	v_mul_f32_e32 v86, 0x33000000, v86
	v_mul_f32_e32 v88, v86, v86
	v_fma_f32 v87, v87, s36, -v88
	v_max_f32_e32 v87, 0, v87
	v_add_f32_e32 v87, 0x3727c5ac, v87
	v_rsq_f32_e32 v87, v87
	v_lshl_add_u64 v[84:85], v[84:85], 0, s[12:13]
	v_lshl_add_u64 v[84:85], v[84:85], 0, s[52:53]
	v_cvt_pk_bf16_f32 v82, v82, v83
	v_cvt_pk_bf16_f32 v83, v96, v97
	v_lshl_add_u64 v[84:85], v[84:85], 0, v[184:185]
	flat_store_dwordx4 v[84:85], v[80:83]
	s_nop 1
; __device__ __forceinline__ u32x4 pack8(f32x4 a, f32x4 b) { u32x4 w; w.x = cvt_pk_bf16(a[0], a[1]); w.y = cvt_pk_bf16(a[2], a[3]); w.z = cvt_pk_bf16(b[0], b[1]); w.w = cvt_pk_bf16(b[2], b[3]); return w; }
;     __device__ __forceinline__ void operator()(EP_ARGS) const {
;     ...
;             for (int m = 0; m < 4; ++m) { const int row = EP_ROW(ai, m); float mu, rstd; ln_unpack(tq[ai][m], mu, rstd); f32x4 h[2];
; #pragma unroll
;                 for (int n = 0; n < 2; ++n) { const float m2 = -mu * rstd;
;                     const f32x4 gg = ln_fold4(acc[ai][0][m][n], cv[0][n], wv[0][n], m2, rstd), uu = ln_fold4(acc[ai][1][m][n], cv[1][n], wv[1][n], m2, rstd);
;                     h[n] = silu_mul4(gg, uu); }
;                 *(u32x4*)(HF + (size_t)row * DFF + u.pn * 128 + wc * 32 + 8 * fq) = pack8(h[0], h[1]); }
	v_mul_f32_e64 v80, v87, -v86
	v_fma_f32 v81, v152, v80, v156
	v_fma_f32 v82, v153, v80, v157
	v_fma_f32 v83, v154, v80, v158
	v_fma_f32 v84, v155, v80, v159
	v_fma_f32 v81, v76, v87, v81
	v_fma_f32 v82, v77, v87, v82
	v_fma_f32 v83, v78, v87, v83
	v_fma_f32 v84, v79, v87, v84
	v_fma_f32 v76, v144, v80, v148
	v_fma_f32 v77, v145, v80, v149
	v_fma_f32 v78, v146, v80, v150
	v_fma_f32 v79, v147, v80, v151
	v_fma_f32 v76, v68, v87, v76
	v_fma_f32 v77, v69, v87, v77
	v_fma_f32 v78, v70, v87, v78
	v_fma_f32 v79, v71, v87, v79
	s_nop 0
	v_mul_f32 v85, 0xbfb8aa3b, v81
	v_mul_f32 v86, 0xbfb8aa3b, v82
	v_mul_f32 v88, 0xbfb8aa3b, v83
	v_mul_f32 v89, 0xbfb8aa3b, v84
	v_exp_f32 v85, v85
	v_exp_f32 v86, v86
	v_exp_f32 v88, v88
	v_exp_f32 v89, v89
	v_mul_f32 v68, v81, v76
	v_mul_f32 v69, v82, v77
	v_mul_f32 v70, v83, v78
	v_mul_f32 v71, v84, v79
	v_add_f32 v85, 1.0, v85
	v_add_f32 v86, 1.0, v86
	v_add_f32 v88, 1.0, v88
	v_add_f32 v89, 1.0, v89
	v_rcp_f32 v85, v85
	v_rcp_f32 v86, v86
	v_rcp_f32 v88, v88
	v_rcp_f32 v89, v89
	s_nop 0
	v_mul_f32 v68, v68, v85
	v_mul_f32 v69, v69, v86
	v_mul_f32 v70, v70, v88
	v_mul_f32 v71, v71, v89
	v_fma_f32 v76, v136, v80, v140
	v_fma_f32 v77, v137, v80, v141
	v_fma_f32 v78, v138, v80, v142
	v_fma_f32 v79, v139, v80, v143
	v_fma_f32 v76, v72, v87, v76
	v_fma_f32 v77, v73, v87, v77
	v_fma_f32 v78, v74, v87, v78
	v_fma_f32 v79, v75, v87, v79
	v_fma_f32 v72, v128, v80, v132
	v_fma_f32 v73, v129, v80, v133
	v_fma_f32 v74, v130, v80, v134
	v_fma_f32 v75, v131, v80, v135
	v_fma_f32 v72, v64, v87, v72
	v_fma_f32 v73, v65, v87, v73
	v_fma_f32 v74, v66, v87, v74
	v_fma_f32 v75, v67, v87, v75
	s_nop 0
	v_mul_f32 v64, 0xbfb8aa3b, v76
	v_mul_f32 v65, 0xbfb8aa3b, v77
	v_mul_f32 v82, 0xbfb8aa3b, v78
	v_mul_f32 v83, 0xbfb8aa3b, v79
	v_exp_f32 v64, v64
	v_exp_f32 v65, v65
	v_exp_f32 v82, v82
	v_exp_f32 v83, v83
	v_mul_f32 v66, v76, v72
	v_mul_f32 v67, v77, v73
	v_mul_f32 v80, v78, v74
	v_mul_f32 v81, v79, v75
	v_add_f32 v64, 1.0, v64
	v_add_f32 v65, 1.0, v65
	v_add_f32 v82, 1.0, v82
	v_add_f32 v83, 1.0, v83
	v_rcp_f32 v64, v64
	v_rcp_f32 v65, v65
	v_rcp_f32 v82, v82
	v_rcp_f32 v83, v83
	s_nop 0
	v_mul_f32 v66, v66, v64
	v_mul_f32 v67, v67, v65
	v_mul_f32 v80, v80, v82
	v_mul_f32 v81, v81, v83
	s_nop 0
	v_cvt_pk_bf16_f32 v64, v68, v69
	v_cvt_pk_bf16_f32 v65, v70, v71
	v_cvt_f32_i32_e32 v70, v167
	v_cvt_f32_u32_e32 v71, v166
	v_mad_i64_i32 v[68:69], s[16:17], v198, s19, v[112:113]
	v_mul_f32_e32 v70, 0x33000000, v70
	v_mul_f32_e32 v72, v70, v70
	v_fma_f32 v71, v71, s36, -v72
	v_max_f32_e32 v71, 0, v71
	v_add_f32_e32 v71, 0x3727c5ac, v71
	v_rsq_f32_e32 v71, v71
	v_lshl_add_u64 v[68:69], v[68:69], 0, s[12:13]
	v_lshl_add_u64 v[68:69], v[68:69], 0, s[52:53]
	v_cvt_pk_bf16_f32 v66, v66, v67
	v_cvt_pk_bf16_f32 v67, v80, v81
	v_lshl_add_u64 v[68:69], v[68:69], 0, v[184:185]
	flat_store_dwordx4 v[68:69], v[64:67]
	s_nop 1
	v_mul_f32_e64 v64, v71, -v70
	v_fma_f32 v65, v152, v64, v156
	v_fma_f32 v66, v153, v64, v157
	v_fma_f32 v67, v154, v64, v158
	v_fma_f32 v68, v155, v64, v159
	v_fma_f32 v65, v60, v71, v65
	v_fma_f32 v66, v61, v71, v66
	v_fma_f32 v67, v62, v71, v67
	v_fma_f32 v68, v63, v71, v68
	v_fma_f32 v60, v144, v64, v148
	v_fma_f32 v61, v145, v64, v149
	v_fma_f32 v62, v146, v64, v150
	v_fma_f32 v63, v147, v64, v151
	v_fma_f32 v60, v52, v71, v60
	v_fma_f32 v61, v53, v71, v61
	v_fma_f32 v62, v54, v71, v62
	v_fma_f32 v63, v55, v71, v63
	s_nop 0
	v_mul_f32 v69, 0xbfb8aa3b, v65
	v_mul_f32 v70, 0xbfb8aa3b, v66
	v_mul_f32 v72, 0xbfb8aa3b, v67
	v_mul_f32 v73, 0xbfb8aa3b, v68
	v_exp_f32 v69, v69
	v_exp_f32 v70, v70
	v_exp_f32 v72, v72
	v_exp_f32 v73, v73
	v_mul_f32 v52, v65, v60
	v_mul_f32 v53, v66, v61
	v_mul_f32 v54, v67, v62
	v_mul_f32 v55, v68, v63
	v_add_f32 v69, 1.0, v69
	v_add_f32 v70, 1.0, v70
	v_add_f32 v72, 1.0, v72
	v_add_f32 v73, 1.0, v73
	v_rcp_f32 v69, v69
	v_rcp_f32 v70, v70
	v_rcp_f32 v72, v72
	v_rcp_f32 v73, v73
	s_nop 0
	v_mul_f32 v52, v52, v69
	v_mul_f32 v53, v53, v70
	v_mul_f32 v54, v54, v72
	v_mul_f32 v55, v55, v73
	v_fma_f32 v60, v136, v64, v140
	v_fma_f32 v61, v137, v64, v141
	v_fma_f32 v62, v138, v64, v142
	v_fma_f32 v63, v139, v64, v143
	v_fma_f32 v60, v56, v71, v60
	v_fma_f32 v61, v57, v71, v61
	v_fma_f32 v62, v58, v71, v62
	v_fma_f32 v63, v59, v71, v63
	v_fma_f32 v56, v128, v64, v132
	v_fma_f32 v57, v129, v64, v133
	v_fma_f32 v58, v130, v64, v134
	v_fma_f32 v59, v131, v64, v135
	v_fma_f32 v56, v48, v71, v56
	v_fma_f32 v57, v49, v71, v57
	v_fma_f32 v58, v50, v71, v58
	v_fma_f32 v59, v51, v71, v59
	s_nop 0
	v_mul_f32 v48, 0xbfb8aa3b, v60
	v_mul_f32 v49, 0xbfb8aa3b, v61
	v_mul_f32 v66, 0xbfb8aa3b, v62
	v_mul_f32 v67, 0xbfb8aa3b, v63
	v_exp_f32 v48, v48
	v_exp_f32 v49, v49
	v_exp_f32 v66, v66
	v_exp_f32 v67, v67
	v_mul_f32 v50, v60, v56
	v_mul_f32 v51, v61, v57
	v_mul_f32 v64, v62, v58
	v_mul_f32 v65, v63, v59
	v_add_f32 v48, 1.0, v48
	v_add_f32 v49, 1.0, v49
	v_add_f32 v66, 1.0, v66
	v_add_f32 v67, 1.0, v67
	v_rcp_f32 v48, v48
	v_rcp_f32 v49, v49
	v_rcp_f32 v66, v66
	v_rcp_f32 v67, v67
	s_nop 0
	v_mul_f32 v50, v50, v48
	v_mul_f32 v51, v51, v49
	v_mul_f32 v64, v64, v66
	v_mul_f32 v65, v65, v67
	s_nop 0
	v_cvt_pk_bf16_f32 v48, v52, v53
	v_cvt_pk_bf16_f32 v49, v54, v55
	v_cvt_f32_i32_e32 v54, v165
	v_cvt_f32_u32_e32 v55, v164
	v_mad_i64_i32 v[52:53], s[16:17], v199, s19, v[112:113]
	v_mul_f32_e32 v54, 0x33000000, v54
	v_mul_f32_e32 v56, v54, v54
	v_fma_f32 v55, v55, s36, -v56
	v_max_f32_e32 v55, 0, v55
	v_add_f32_e32 v55, 0x3727c5ac, v55
	v_rsq_f32_e32 v55, v55
	v_lshl_add_u64 v[52:53], v[52:53], 0, s[12:13]
	v_lshl_add_u64 v[52:53], v[52:53], 0, s[52:53]
	v_cvt_pk_bf16_f32 v50, v50, v51
	v_cvt_pk_bf16_f32 v51, v64, v65
; __device__ __forceinline__ u32x4 pack8(f32x4 a, f32x4 b) { u32x4 w; w.x = cvt_pk_bf16(a[0], a[1]); w.y = cvt_pk_bf16(a[2], a[3]); w.z = cvt_pk_bf16(b[0], b[1]); w.w = cvt_pk_bf16(b[2], b[3]); return w; }
;     __device__ __forceinline__ void operator()(EP_ARGS) const {
;     ...
;             for (int m = 0; m < 4; ++m) { const int row = EP_ROW(ai, m); float mu, rstd; ln_unpack(tq[ai][m], mu, rstd); f32x4 h[2];
; #pragma unroll
;                 for (int n = 0; n < 2; ++n) { const float m2 = -mu * rstd;
;                     const f32x4 gg = ln_fold4(acc[ai][0][m][n], cv[0][n], wv[0][n], m2, rstd), uu = ln_fold4(acc[ai][1][m][n], cv[1][n], wv[1][n], m2, rstd);
;                     h[n] = silu_mul4(gg, uu); }
;                 *(u32x4*)(HF + (size_t)row * DFF + u.pn * 128 + wc * 32 + 8 * fq) = pack8(h[0], h[1]); }
	v_lshl_add_u64 v[52:53], v[52:53], 0, v[184:185]
	flat_store_dwordx4 v[52:53], v[48:51]
	s_nop 1
	v_mul_f32_e64 v48, v55, -v54
	v_fma_f32 v49, v152, v48, v156
	v_fma_f32 v50, v153, v48, v157
	v_fma_f32 v51, v154, v48, v158
	v_fma_f32 v52, v155, v48, v159
	v_fma_f32 v49, v44, v55, v49
	v_fma_f32 v50, v45, v55, v50
	v_fma_f32 v51, v46, v55, v51
	v_fma_f32 v52, v47, v55, v52
	v_fma_f32 v44, v144, v48, v148
	v_fma_f32 v45, v145, v48, v149
	v_fma_f32 v46, v146, v48, v150
	v_fma_f32 v47, v147, v48, v151
	v_fma_f32 v44, v36, v55, v44
	v_fma_f32 v45, v37, v55, v45
	v_fma_f32 v46, v38, v55, v46
	v_fma_f32 v47, v39, v55, v47
	s_nop 0
	v_mul_f32 v53, 0xbfb8aa3b, v49
	v_mul_f32 v54, 0xbfb8aa3b, v50
	v_mul_f32 v56, 0xbfb8aa3b, v51
	v_mul_f32 v57, 0xbfb8aa3b, v52
	v_exp_f32 v53, v53
	v_exp_f32 v54, v54
	v_exp_f32 v56, v56
	v_exp_f32 v57, v57
	v_mul_f32 v36, v49, v44
	v_mul_f32 v37, v50, v45
	v_mul_f32 v38, v51, v46
	v_mul_f32 v39, v52, v47
	v_add_f32 v53, 1.0, v53
	v_add_f32 v54, 1.0, v54
	v_add_f32 v56, 1.0, v56
	v_add_f32 v57, 1.0, v57
	v_rcp_f32 v53, v53
	v_rcp_f32 v54, v54
	v_rcp_f32 v56, v56
	v_rcp_f32 v57, v57
	s_nop 0
	v_mul_f32 v36, v36, v53
	v_mul_f32 v37, v37, v54
	v_mul_f32 v38, v38, v56
	v_mul_f32 v39, v39, v57
	v_fma_f32 v44, v136, v48, v140
	v_fma_f32 v45, v137, v48, v141
	v_fma_f32 v46, v138, v48, v142
	v_fma_f32 v47, v139, v48, v143
	v_fma_f32 v44, v40, v55, v44
	v_fma_f32 v45, v41, v55, v45
	v_fma_f32 v46, v42, v55, v46
	v_fma_f32 v47, v43, v55, v47
	v_fma_f32 v40, v128, v48, v132
	v_fma_f32 v41, v129, v48, v133
	v_fma_f32 v42, v130, v48, v134
	v_fma_f32 v43, v131, v48, v135
	v_fma_f32 v40, v32, v55, v40
	v_fma_f32 v41, v33, v55, v41
	v_fma_f32 v42, v34, v55, v42
	v_fma_f32 v43, v35, v55, v43
	s_nop 0
	v_mul_f32 v32, 0xbfb8aa3b, v44
	v_mul_f32 v33, 0xbfb8aa3b, v45
	v_mul_f32 v50, 0xbfb8aa3b, v46
	v_mul_f32 v51, 0xbfb8aa3b, v47
	v_exp_f32 v32, v32
	v_exp_f32 v33, v33
	v_exp_f32 v50, v50
	v_exp_f32 v51, v51
	v_mul_f32 v34, v44, v40
	v_mul_f32 v35, v45, v41
	v_mul_f32 v48, v46, v42
	v_mul_f32 v49, v47, v43
	v_add_f32 v32, 1.0, v32
	v_add_f32 v33, 1.0, v33
	v_add_f32 v50, 1.0, v50
	v_add_f32 v51, 1.0, v51
	v_rcp_f32 v32, v32
	v_rcp_f32 v33, v33
	v_rcp_f32 v50, v50
	v_rcp_f32 v51, v51
	s_nop 0
	v_mul_f32 v34, v34, v32
	v_mul_f32 v35, v35, v33
	v_mul_f32 v48, v48, v50
	v_mul_f32 v49, v49, v51
	s_nop 0
	v_cvt_pk_bf16_f32 v32, v36, v37
	v_cvt_pk_bf16_f32 v33, v38, v39
	v_cvt_f32_i32_e32 v38, v163
	v_cvt_f32_u32_e32 v39, v162
	v_mad_i64_i32 v[36:37], s[16:17], v182, s19, v[112:113]
	v_mul_f32_e32 v38, 0x33000000, v38
	v_mul_f32_e32 v40, v38, v38
	v_fma_f32 v39, v39, s36, -v40
	v_max_f32_e32 v39, 0, v39
	v_add_f32_e32 v39, 0x3727c5ac, v39
	v_rsq_f32_e32 v39, v39
	v_lshl_add_u64 v[36:37], v[36:37], 0, s[12:13]
	v_lshl_add_u64 v[36:37], v[36:37], 0, s[52:53]
	v_cvt_pk_bf16_f32 v34, v34, v35
	v_cvt_pk_bf16_f32 v35, v48, v49
	v_lshl_add_u64 v[36:37], v[36:37], 0, v[184:185]
	flat_store_dwordx4 v[36:37], v[32:35]
	s_nop 1
	v_mul_f32_e64 v32, v39, -v38
	v_fma_f32 v33, v152, v32, v156
	v_fma_f32 v34, v153, v32, v157
	v_fma_f32 v35, v154, v32, v158
	v_fma_f32 v36, v155, v32, v159
	v_fma_f32 v33, v28, v39, v33
	v_fma_f32 v34, v29, v39, v34
	v_fma_f32 v35, v30, v39, v35
	v_fma_f32 v36, v31, v39, v36
	v_fma_f32 v28, v144, v32, v148
	v_fma_f32 v29, v145, v32, v149
	v_fma_f32 v30, v146, v32, v150
	v_fma_f32 v31, v147, v32, v151
	v_fma_f32 v28, v20, v39, v28
	v_fma_f32 v29, v21, v39, v29
	v_fma_f32 v30, v22, v39, v30
	v_fma_f32 v31, v23, v39, v31
	s_nop 0
	v_mul_f32 v37, 0xbfb8aa3b, v33
	v_mul_f32 v38, 0xbfb8aa3b, v34
	v_mul_f32 v40, 0xbfb8aa3b, v35
	v_mul_f32 v41, 0xbfb8aa3b, v36
	v_exp_f32 v37, v37
	v_exp_f32 v38, v38
	v_exp_f32 v40, v40
	v_exp_f32 v41, v41
	v_mul_f32 v20, v33, v28
	v_mul_f32 v21, v34, v29
	v_mul_f32 v22, v35, v30
	v_mul_f32 v23, v36, v31
	v_add_f32 v37, 1.0, v37
	v_add_f32 v38, 1.0, v38
	v_add_f32 v40, 1.0, v40
	v_add_f32 v41, 1.0, v41
	v_rcp_f32 v37, v37
	v_rcp_f32 v38, v38
	v_rcp_f32 v40, v40
	v_rcp_f32 v41, v41
	s_nop 0
	v_mul_f32 v20, v20, v37
	v_mul_f32 v21, v21, v38
	v_mul_f32 v22, v22, v40
	v_mul_f32 v23, v23, v41
	v_fma_f32 v28, v136, v32, v140
	v_fma_f32 v29, v137, v32, v141
	v_fma_f32 v30, v138, v32, v142
	v_fma_f32 v31, v139, v32, v143
	v_fma_f32 v28, v24, v39, v28
; __device__ __forceinline__ u32x4 pack8(f32x4 a, f32x4 b) { u32x4 w; w.x = cvt_pk_bf16(a[0], a[1]); w.y = cvt_pk_bf16(a[2], a[3]); w.z = cvt_pk_bf16(b[0], b[1]); w.w = cvt_pk_bf16(b[2], b[3]); return w; }
; #define PG8_BAR __builtin_amdgcn_s_barrier()
; template <class Epi>
; __device__ __forceinline__ void gemm_phase(LAS unsigned char* lds, const Gemm g, const StaticOrder& S, const Epi& E, int wave_) {
;     ...
;         if (wr == 0) PG8_BAR;
;         E(acc, cur, wr, wc, fr, fq);
;         if (!has_next) break;
; #pragma unroll
;         for (int a = 0; a < 2; ++a)
; #pragma unroll
;             for (int b = 0; b < 2; ++b)
; #pragma unroll
;                 for (int m = 0; m < 4; ++m)
; #pragma unroll
;                     for (int n = 0; n < 2; ++n) acc[a][b][m][n] = (f32x4){0.f, 0.f, 0.f, 0.f};
;         cur = nxt; cA = nA; cB = nB; ++ui;
;         if (wr == 1) PG8_BAR;
;     __device__ __forceinline__ void operator()(EP_ARGS) const {
;     ...
;             for (int m = 0; m < 4; ++m) { const int row = EP_ROW(ai, m); float mu, rstd; ln_unpack(tq[ai][m], mu, rstd); f32x4 h[2];
; #pragma unroll
;                 for (int n = 0; n < 2; ++n) { const float m2 = -mu * rstd;
;                     const f32x4 gg = ln_fold4(acc[ai][0][m][n], cv[0][n], wv[0][n], m2, rstd), uu = ln_fold4(acc[ai][1][m][n], cv[1][n], wv[1][n], m2, rstd);
;                     h[n] = silu_mul4(gg, uu); }
;                 *(u32x4*)(HF + (size_t)row * DFF + u.pn * 128 + wc * 32 + 8 * fq) = pack8(h[0], h[1]); }
	v_fma_f32 v29, v25, v39, v29
	v_fma_f32 v30, v26, v39, v30
	v_fma_f32 v31, v27, v39, v31
	v_fma_f32 v24, v128, v32, v132
	v_fma_f32 v25, v129, v32, v133
	v_fma_f32 v26, v130, v32, v134
	v_fma_f32 v27, v131, v32, v135
	v_fma_f32 v24, v16, v39, v24
	v_fma_f32 v25, v17, v39, v25
	v_fma_f32 v26, v18, v39, v26
	v_fma_f32 v27, v19, v39, v27
	s_nop 0
	v_mul_f32 v16, 0xbfb8aa3b, v28
	v_mul_f32 v17, 0xbfb8aa3b, v29
	v_mul_f32 v34, 0xbfb8aa3b, v30
	v_mul_f32 v35, 0xbfb8aa3b, v31
	v_exp_f32 v16, v16
	v_exp_f32 v17, v17
	v_exp_f32 v34, v34
	v_exp_f32 v35, v35
	v_mul_f32 v18, v28, v24
	v_mul_f32 v19, v29, v25
	v_mul_f32 v32, v30, v26
	v_mul_f32 v33, v31, v27
	v_add_f32 v16, 1.0, v16
	v_add_f32 v17, 1.0, v17
	v_add_f32 v34, 1.0, v34
	v_add_f32 v35, 1.0, v35
	v_rcp_f32 v16, v16
	v_rcp_f32 v17, v17
	v_rcp_f32 v34, v34
	v_rcp_f32 v35, v35
	s_nop 0
	v_mul_f32 v18, v18, v16
	v_mul_f32 v19, v19, v17
	v_mul_f32 v32, v32, v34
	v_mul_f32 v33, v33, v35
	s_nop 0
	v_cvt_pk_bf16_f32 v16, v20, v21
	v_cvt_pk_bf16_f32 v17, v22, v23
	v_cvt_f32_i32_e32 v22, v161
	v_cvt_f32_u32_e32 v23, v160
	v_mad_i64_i32 v[20:21], s[16:17], v181, s19, v[112:113]
	v_mul_f32_e32 v22, 0x33000000, v22
	v_mul_f32_e32 v24, v22, v22
	v_fma_f32 v23, v23, s36, -v24
	v_max_f32_e32 v23, 0, v23
	v_add_f32_e32 v23, 0x3727c5ac, v23
	v_rsq_f32_e32 v23, v23
	v_lshl_add_u64 v[20:21], v[20:21], 0, s[12:13]
	v_lshl_add_u64 v[20:21], v[20:21], 0, s[52:53]
	v_cvt_pk_bf16_f32 v18, v18, v19
	v_cvt_pk_bf16_f32 v19, v32, v33
	v_lshl_add_u64 v[20:21], v[20:21], 0, v[184:185]
	flat_store_dwordx4 v[20:21], v[16:19]
	s_nop 1
	v_mul_f32_e64 v16, v23, -v22
	v_fma_f32 v17, v152, v16, v156
	v_fma_f32 v18, v153, v16, v157
	v_fma_f32 v19, v154, v16, v158
	v_fma_f32 v20, v155, v16, v159
	v_fma_f32 v17, v12, v23, v17
	v_fma_f32 v18, v13, v23, v18
	v_fma_f32 v19, v14, v23, v19
	v_fma_f32 v20, v15, v23, v20
	v_fma_f32 v12, v144, v16, v148
	v_fma_f32 v13, v145, v16, v149
	v_fma_f32 v14, v146, v16, v150
	v_fma_f32 v15, v147, v16, v151
	v_fma_f32 v12, v4, v23, v12
	v_fma_f32 v13, v5, v23, v13
	v_fma_f32 v14, v6, v23, v14
	v_fma_f32 v15, v7, v23, v15
	s_nop 0
	v_mul_f32 v21, 0xbfb8aa3b, v17
	v_mul_f32 v22, 0xbfb8aa3b, v18
	v_mul_f32 v24, 0xbfb8aa3b, v19
	v_mul_f32 v25, 0xbfb8aa3b, v20
	v_exp_f32 v21, v21
	v_exp_f32 v22, v22
	v_exp_f32 v24, v24
	v_exp_f32 v25, v25
	v_mul_f32 v4, v17, v12
	v_mul_f32 v5, v18, v13
	v_mul_f32 v6, v19, v14
	v_mul_f32 v7, v20, v15
	v_add_f32 v21, 1.0, v21
	v_add_f32 v22, 1.0, v22
	v_add_f32 v24, 1.0, v24
	v_add_f32 v25, 1.0, v25
	v_rcp_f32 v21, v21
	v_rcp_f32 v22, v22
	v_rcp_f32 v24, v24
	v_rcp_f32 v25, v25
	s_nop 0
	v_mul_f32 v4, v4, v21
	v_mul_f32 v5, v5, v22
	v_mul_f32 v6, v6, v24
	v_mul_f32 v7, v7, v25
	v_fma_f32 v12, v136, v16, v140
	v_fma_f32 v13, v137, v16, v141
	v_fma_f32 v14, v138, v16, v142
	v_fma_f32 v15, v139, v16, v143
	v_fma_f32 v12, v8, v23, v12
	v_fma_f32 v13, v9, v23, v13
	v_fma_f32 v14, v10, v23, v14
	v_fma_f32 v15, v11, v23, v15
	v_fma_f32 v8, v128, v16, v132
	v_fma_f32 v9, v129, v16, v133
	v_fma_f32 v10, v130, v16, v134
	v_fma_f32 v11, v131, v16, v135
	v_fma_f32 v8, v0, v23, v8
	v_fma_f32 v9, v1, v23, v9
	v_fma_f32 v10, v2, v23, v10
	v_fma_f32 v11, v3, v23, v11
	s_nop 0
	v_mul_f32 v0, 0xbfb8aa3b, v12
	v_mul_f32 v1, 0xbfb8aa3b, v13
	v_mul_f32 v18, 0xbfb8aa3b, v14
	v_mul_f32 v19, 0xbfb8aa3b, v15
	v_exp_f32 v0, v0
	v_exp_f32 v1, v1
	v_exp_f32 v18, v18
	v_exp_f32 v19, v19
	v_mul_f32 v2, v12, v8
	v_mul_f32 v3, v13, v9
	v_mul_f32 v16, v14, v10
	v_mul_f32 v17, v15, v11
	v_add_f32 v0, 1.0, v0
	v_add_f32 v1, 1.0, v1
	v_add_f32 v18, 1.0, v18
	v_add_f32 v19, 1.0, v19
	v_rcp_f32 v0, v0
	v_rcp_f32 v1, v1
	v_rcp_f32 v18, v18
	v_rcp_f32 v19, v19
	s_nop 0
	v_mul_f32 v2, v2, v0
	v_mul_f32 v3, v3, v1
	v_mul_f32 v16, v16, v18
	v_mul_f32 v17, v17, v19
	s_nop 0
	v_cvt_pk_bf16_f32 v0, v4, v5
	v_mad_i64_i32 v[4:5], s[16:17], v180, s19, v[112:113]
	v_lshl_add_u64 v[4:5], v[4:5], 0, s[12:13]
	v_lshl_add_u64 v[4:5], v[4:5], 0, s[52:53]
	v_lshl_add_u64 v[4:5], v[4:5], 0, v[184:185]
	s_mov_b64 s[12:13], -1
	v_cvt_pk_bf16_f32 v1, v6, v7
	v_cvt_pk_bf16_f32 v2, v2, v3
	v_cvt_pk_bf16_f32 v3, v16, v17
	flat_store_dwordx4 v[4:5], v[0:3]
	s_setprio 0
	s_cbranch_vccnz .LBB0_1318
	s_and_b64 vcc, exec, s[38:39]
	s_cbranch_vccnz .LBB0_1317
	s_barrier
	s_branch .LBB0_1317

; __device__ __forceinline__ u32x4 pack8(f32x4 a, f32x4 b) { u32x4 w; w.x = cvt_pk_bf16(a[0], a[1]); w.y = cvt_pk_bf16(a[2], a[3]); w.z = cvt_pk_bf16(b[0], b[1]); w.w = cvt_pk_bf16(b[2], b[3]); return w; }
; #define PG8_BAR __builtin_amdgcn_s_barrier()
; template <class Epi>
; __device__ __forceinline__ void gemm_phase(LAS unsigned char* lds, const Gemm g, const StaticOrder& S, const Epi& E, int wave_) {
;     ...
;         if (wr == 0) PG8_BAR;
;         E(acc, cur, wr, wc, fr, fq);
;         if (!has_next) break;
;     __device__ __forceinline__ void operator()(EP_ARGS) const {
; #pragma unroll
;         for (int ai = 0; ai < 2; ++ai)
; #pragma unroll
;             for (int m = 0; m < 4; ++m) { const int row = EP_ROW(ai, m);
; #pragma unroll
;                 for (int bj = 0; bj < 2; ++bj) *(u32x4*)(O + (size_t)row * ldc + EP_COL8(bj)) = pack8(acc[ai][bj][m][0], acc[ai][bj][m][1]); }
;     }
.Lpeel_exit_2:
	v_readlane_b32 s12, v253, 13
	v_readlane_b32 s13, v253, 14
	s_and_b64 vcc, exec, s[12:13]
	v_readlane_b32 s61, v255, 16
	s_cbranch_vccz .LBB0_1345
	s_barrier
	s_setprio 1
.LBB0_1345:
	v_lshl_add_u32 v128, s60, 8, v134
	v_lshl_or_b32 v138, s55, 8, v137
	v_ashrrev_i32_e32 v129, 31, v128
	v_cvt_pk_bf16_f32 v124, v124, v125
	v_cvt_pk_bf16_f32 v125, v126, v127
	v_cvt_pk_bf16_f32 v126, v120, v121
	v_lshlrev_b64 v[120:121], 12, v[128:129]
	v_ashrrev_i32_e32 v139, 31, v138
	v_cvt_pk_bf16_f32 v127, v122, v123
	v_lshl_add_u64 v[122:123], s[4:5], 0, v[120:121]
	v_lshlrev_b64 v[120:121], 1, v[138:139]
	v_lshl_add_u64 v[122:123], v[122:123], 0, v[120:121]
	flat_store_dwordx4 v[122:123], v[124:127]
	v_cvt_pk_bf16_f32 v112, v112, v113
	v_cvt_pk_bf16_f32 v113, v114, v115
	v_cvt_pk_bf16_f32 v114, v104, v105
	v_cvt_pk_bf16_f32 v115, v106, v107
	flat_store_dwordx4 v[122:123], v[112:115] offset:256
	v_cvt_pk_bf16_f32 v104, v116, v117
	v_cvt_pk_bf16_f32 v105, v118, v119
	v_cvt_pk_bf16_f32 v106, v108, v109
	v_cvt_pk_bf16_f32 v107, v110, v111
	s_andn2_b64 vcc, exec, s[42:43]
	s_nop 0
	v_or_b32_e32 v112, 16, v128
	v_ashrrev_i32_e32 v113, 31, v112
	v_lshlrev_b64 v[108:109], 12, v[112:113]
	v_lshl_add_u64 v[108:109], s[4:5], 0, v[108:109]
	v_lshl_add_u64 v[108:109], v[108:109], 0, v[120:121]
	flat_store_dwordx4 v[108:109], v[104:107]
	v_cvt_pk_bf16_f32 v96, v96, v97
	v_cvt_pk_bf16_f32 v97, v98, v99
	v_cvt_pk_bf16_f32 v98, v88, v89
	v_cvt_pk_bf16_f32 v99, v90, v91
	flat_store_dwordx4 v[108:109], v[96:99] offset:256
	v_cvt_pk_bf16_f32 v88, v100, v101
	v_cvt_pk_bf16_f32 v89, v102, v103
	v_cvt_pk_bf16_f32 v90, v92, v93
	v_cvt_pk_bf16_f32 v91, v94, v95
	s_mov_b64 s[12:13], -1
	s_nop 0
	v_or_b32_e32 v96, 32, v128
	v_ashrrev_i32_e32 v97, 31, v96
	v_lshlrev_b64 v[92:93], 12, v[96:97]
	v_lshl_add_u64 v[92:93], s[4:5], 0, v[92:93]
	v_lshl_add_u64 v[92:93], v[92:93], 0, v[120:121]
	flat_store_dwordx4 v[92:93], v[88:91]
	v_cvt_pk_bf16_f32 v80, v80, v81
	v_cvt_pk_bf16_f32 v81, v82, v83
	v_cvt_pk_bf16_f32 v82, v72, v73
	v_cvt_pk_bf16_f32 v83, v74, v75
	flat_store_dwordx4 v[92:93], v[80:83] offset:256
	v_cvt_pk_bf16_f32 v72, v84, v85
	v_cvt_pk_bf16_f32 v73, v86, v87
	v_cvt_pk_bf16_f32 v74, v76, v77
	v_cvt_pk_bf16_f32 v75, v78, v79
	s_nop 1
	v_or_b32_e32 v80, 48, v128
	v_ashrrev_i32_e32 v81, 31, v80
	v_lshlrev_b64 v[76:77], 12, v[80:81]
	v_lshl_add_u64 v[76:77], s[4:5], 0, v[76:77]
	v_lshl_add_u64 v[76:77], v[76:77], 0, v[120:121]
	flat_store_dwordx4 v[76:77], v[72:75]
	v_cvt_pk_bf16_f32 v68, v68, v69
	v_cvt_pk_bf16_f32 v69, v70, v71
	v_cvt_pk_bf16_f32 v70, v64, v65
	v_add_u32_e32 v64, 0x80, v128
	v_ashrrev_i32_e32 v65, 31, v64
	v_cvt_pk_bf16_f32 v71, v66, v67
	flat_store_dwordx4 v[76:77], v[68:71] offset:256
	v_cvt_pk_bf16_f32 v60, v60, v61
	v_cvt_pk_bf16_f32 v61, v62, v63
	v_cvt_pk_bf16_f32 v62, v56, v57
	v_lshlrev_b64 v[56:57], 12, v[64:65]
	v_lshl_add_u64 v[56:57], s[4:5], 0, v[56:57]
	v_lshl_add_u64 v[56:57], v[56:57], 0, v[120:121]
	v_cvt_pk_bf16_f32 v63, v58, v59
	flat_store_dwordx4 v[56:57], v[60:63]
	v_cvt_pk_bf16_f32 v48, v48, v49
	v_cvt_pk_bf16_f32 v49, v50, v51
	v_cvt_pk_bf16_f32 v50, v40, v41
	v_cvt_pk_bf16_f32 v51, v42, v43
	flat_store_dwordx4 v[56:57], v[48:51] offset:256
	v_cvt_pk_bf16_f32 v40, v52, v53
	v_cvt_pk_bf16_f32 v41, v54, v55
	v_cvt_pk_bf16_f32 v42, v44, v45
	v_cvt_pk_bf16_f32 v43, v46, v47
	s_nop 1
	v_add_u32_e32 v48, 0x90, v128
	v_ashrrev_i32_e32 v49, 31, v48
	v_lshlrev_b64 v[44:45], 12, v[48:49]
	v_lshl_add_u64 v[44:45], s[4:5], 0, v[44:45]
	v_lshl_add_u64 v[44:45], v[44:45], 0, v[120:121]
	flat_store_dwordx4 v[44:45], v[40:43]
	v_cvt_pk_bf16_f32 v32, v32, v33
	v_cvt_pk_bf16_f32 v33, v34, v35
	v_cvt_pk_bf16_f32 v34, v24, v25
	v_cvt_pk_bf16_f32 v35, v26, v27
	flat_store_dwordx4 v[44:45], v[32:35] offset:256
	v_cvt_pk_bf16_f32 v24, v36, v37
	v_cvt_pk_bf16_f32 v25, v38, v39
	v_cvt_pk_bf16_f32 v26, v28, v29
	v_cvt_pk_bf16_f32 v27, v30, v31
	s_nop 1
	v_add_u32_e32 v32, 0xa0, v128
	v_ashrrev_i32_e32 v33, 31, v32
	v_lshlrev_b64 v[28:29], 12, v[32:33]
	v_lshl_add_u64 v[28:29], s[4:5], 0, v[28:29]
	v_lshl_add_u64 v[28:29], v[28:29], 0, v[120:121]
	flat_store_dwordx4 v[28:29], v[24:27]
	v_cvt_pk_bf16_f32 v16, v16, v17
	v_cvt_pk_bf16_f32 v17, v18, v19
	v_cvt_pk_bf16_f32 v18, v8, v9
	v_cvt_pk_bf16_f32 v19, v10, v11
	flat_store_dwordx4 v[28:29], v[16:19] offset:256
	v_cvt_pk_bf16_f32 v8, v20, v21
	v_cvt_pk_bf16_f32 v9, v22, v23
	v_cvt_pk_bf16_f32 v10, v12, v13
	v_cvt_pk_bf16_f32 v11, v14, v15
	s_nop 1
	v_add_u32_e32 v16, 0xb0, v128
	v_ashrrev_i32_e32 v17, 31, v16
	v_lshlrev_b64 v[12:13], 12, v[16:17]
	v_lshl_add_u64 v[12:13], s[4:5], 0, v[12:13]
	v_lshl_add_u64 v[12:13], v[12:13], 0, v[120:121]
	flat_store_dwordx4 v[12:13], v[8:11]
	v_cvt_pk_bf16_f32 v4, v4, v5
	v_cvt_pk_bf16_f32 v5, v6, v7
	v_cvt_pk_bf16_f32 v6, v0, v1
	v_cvt_pk_bf16_f32 v7, v2, v3
	flat_store_dwordx4 v[12:13], v[4:7] offset:256
	s_setprio 0
	s_cbranch_vccnz .LBB0_1334
	s_and_b64 vcc, exec, s[38:39]
	s_cbranch_vccnz .LBB0_1333
	s_barrier
	s_branch .LBB0_1333

; #define PG8_BAR __builtin_amdgcn_s_barrier()
; __device__ __forceinline__ float fq_sum(float s) { return x16x32_sum(s); }
; template <class Epi>
; __device__ __forceinline__ void gemm_phase(LAS unsigned char* lds, const Gemm g, const StaticOrder& S, const Epi& E, int wave_) {
;     ...
;         if (wr == 0) PG8_BAR;
;         E(acc, cur, wr, wc, fr, fq);
;         if (!has_next) break;
; #pragma unroll
;         for (int a = 0; a < 2; ++a)
; #pragma unroll
;             for (int b = 0; b < 2; ++b)
; #pragma unroll
;                 for (int m = 0; m < 4; ++m)
; #pragma unroll
;                     for (int n = 0; n < 2; ++n) acc[a][b][m][n] = (f32x4){0.f, 0.f, 0.f, 0.f};
;         cur = nxt; cA = nA; cB = nB; ++ui;
;         if (wr == 1) PG8_BAR;
;     __device__ __forceinline__ void operator()(EP_ARGS) const {
;     ...
;                 s = fq_sum(s); q = fq_sum(q);
;                 if (fq == 0) atomic_add_stat(st_out + (size_t)row, s, q); }
;             asm volatile("" ::: "memory"); }
.LBB0_1571:
	s_or_b64 exec, exec, s[12:13]
	s_and_b64 vcc, exec, s[44:45]
	s_mov_b64 s[12:13], -1
	s_setprio 0
	s_cbranch_vccnz .LBB0_1540
	s_and_b64 vcc, exec, s[38:39]
	s_cbranch_vccnz .LBB0_1539
	s_barrier
	s_branch .LBB0_1539

; #define PG8_BAR __builtin_amdgcn_s_barrier()
; template <class Epi>
; __device__ __forceinline__ void gemm_phase(LAS unsigned char* lds, const Gemm g, const StaticOrder& S, const Epi& E, int wave_) {
;     ...
;         if (wr == 0) PG8_BAR;
;         E(acc, cur, wr, wc, fr, fq);
;         if (!has_next) break;
; #pragma unroll
;         for (int a = 0; a < 2; ++a)
; #pragma unroll
;             for (int b = 0; b < 2; ++b)
; #pragma unroll
;                 for (int m = 0; m < 4; ++m)
; #pragma unroll
;                     for (int n = 0; n < 2; ++n) acc[a][b][m][n] = (f32x4){0.f, 0.f, 0.f, 0.f};
;         cur = nxt; cA = nA; cB = nB; ++ui;
;         if (wr == 1) PG8_BAR;
.LBB0_1891:
	s_andn2_b64 vcc, exec, s[44:45]
	s_mov_b64 s[12:13], -1
	s_setprio 0
	s_cbranch_vccnz .LBB0_1768
	s_and_b64 vcc, exec, s[38:39]
	s_cbranch_vccnz .LBB0_1767
	s_barrier
	s_branch .LBB0_1767
